# prologue: x f32 -> hb bf16 + row sums fast pre-pass (32 rows per wave in 8 double-buffered blocks of 4, DPP+2 bpermute reductions, cvt_pk_bf16), compiler loop keeps only the memory row
# baseline (speedup 1.0000x reference)
; __device__ __forceinline__ unsigned pk2(float lo, float hi) { return f2bf(lo) | (f2bf(hi) << 16); }
; #define lane (hw_lane())
; __device__ __forceinline__ void prologue(const Args& a, LAS unsigned char* lds, int gw, int NGW, int lane, int wave) {
;     ...
;         for (int m = gw; m < M + MMEM; m += NGW) {
;             const bool is_mem = m >= M; const int row = is_mem ? m - M : m;
;             f32x4 v[4]; float s = 0.f;
; #pragma unroll
;             for (int j = 0; j < 4; ++j) v[j] = nv[j];
;             { const int mn = m + NGW; if (mn < M + MMEM) { const f32x4* xr = (const f32x4*)((mn >= M ? a.in[I_MEM] + (size_t)(mn - M) * D : a.in[I_X] + (size_t)mn * D)) + lane;
; #pragma unroll
;                 for (int j = 0; j < 4; ++j) nv[j] = __builtin_nontemporal_load(xr + 64 * j); } }
; #pragma unroll
;             for (int j = 0; j < 4; ++j) s += (v[j].x * v[j].x + v[j].y * v[j].y) + (v[j].z * v[j].z + v[j].w * v[j].w);
;             s = wave_sum(s);
;             float sc = 1.f;
;             if (is_mem) sc = __builtin_amdgcn_rsqf(s * (1.0f / D) + EPS);
;             else if (lane < 16) slots[(size_t)row * 16 + lane] = lane == 0 ? s : 0.f;
;             v2u* o8 = (v2u*)((is_mem ? MEMN : HB) + (size_t)row * D) + lane;
; #pragma unroll
;             for (int j = 0; j < 4; ++j) { v2u o; o.x = pk2(v[j].x * sc, v[j].y * sc); o.y = pk2(v[j].z * sc, v[j].w * sc); o8[64 * j] = o; }
.LBB0_199:
	s_or_b64 exec, exec, s[0:1]
	s_mov_b32 s98, 0
	s_cmp_lg_u32 s38, 0x800
	s_cbranch_scc1 .Lxh_skip
	s_cmp_ge_u32 s72, 0x800
	s_cbranch_scc1 .Lxh_skip
	v_readlane_b32 s10, v253, 20
	v_readlane_b32 s11, v253, 21
	s_lshl_b32 s0, s72, 12
	s_lshl_b32 s1, s72, 11
	s_lshl_b32 s2, s72, 6
	v_lshlrev_b32_e32 v1, 4, v36
	v_lshlrev_b32_e32 v2, 3, v36
	v_lshlrev_b32_e32 v3, 2, v36
	s_add_u32 s10, s10, s0
	s_addc_u32 s11, s11, 0
	s_add_u32 s12, s58, 0x7100000
	s_addc_u32 s13, s59, 0
	s_add_u32 s14, s58, 0x5500000
	s_addc_u32 s15, s59, 0
	v_xor_b32_e32 v4, 16, v36
	v_xor_b32_e32 v5, 32, v36
	s_add_u32 s12, s12, s1
	s_addc_u32 s13, s13, 0
	s_add_u32 s14, s14, s2
	s_addc_u32 s15, s15, 0
	v_lshlrev_b32_e32 v4, 2, v4
	v_lshlrev_b32_e32 v5, 2, v5
	v_mov_b32_e32 v6, 0
	v_cmp_gt_u32_e64 s[4:5], 16, v36
	v_cmp_eq_u32_e64 s[16:17], 0, v36
	global_load_dwordx4 v[40:43], v1, s[10:11] nt
	global_load_dwordx4 v[44:47], v1, s[10:11] offset:1024 nt
	global_load_dwordx4 v[48:51], v1, s[10:11] offset:2048 nt
	global_load_dwordx4 v[52:55], v1, s[10:11] offset:3072 nt
	s_add_u32 s10, s10, 0x800000
	s_addc_u32 s11, s11, 0
	global_load_dwordx4 v[56:59], v1, s[10:11] nt
	global_load_dwordx4 v[60:63], v1, s[10:11] offset:1024 nt
	global_load_dwordx4 v[64:67], v1, s[10:11] offset:2048 nt
	global_load_dwordx4 v[68:71], v1, s[10:11] offset:3072 nt
	s_add_u32 s10, s10, 0x800000
	s_addc_u32 s11, s11, 0
	global_load_dwordx4 v[72:75], v1, s[10:11] nt
	global_load_dwordx4 v[76:79], v1, s[10:11] offset:1024 nt
	global_load_dwordx4 v[80:83], v1, s[10:11] offset:2048 nt
	global_load_dwordx4 v[84:87], v1, s[10:11] offset:3072 nt
	s_add_u32 s10, s10, 0x800000
	s_addc_u32 s11, s11, 0
	global_load_dwordx4 v[88:91], v1, s[10:11] nt
	global_load_dwordx4 v[92:95], v1, s[10:11] offset:1024 nt
	global_load_dwordx4 v[96:99], v1, s[10:11] offset:2048 nt
	global_load_dwordx4 v[100:103], v1, s[10:11] offset:3072 nt
	s_add_u32 s10, s10, 0x800000
	s_addc_u32 s11, s11, 0
	global_load_dwordx4 v[160:163], v1, s[10:11] nt
	global_load_dwordx4 v[164:167], v1, s[10:11] offset:1024 nt
	global_load_dwordx4 v[168:171], v1, s[10:11] offset:2048 nt
	global_load_dwordx4 v[172:175], v1, s[10:11] offset:3072 nt
	s_add_u32 s10, s10, 0x800000
	s_addc_u32 s11, s11, 0
	global_load_dwordx4 v[176:179], v1, s[10:11] nt
	global_load_dwordx4 v[180:183], v1, s[10:11] offset:1024 nt
	global_load_dwordx4 v[184:187], v1, s[10:11] offset:2048 nt
	global_load_dwordx4 v[188:191], v1, s[10:11] offset:3072 nt
	s_add_u32 s10, s10, 0x800000
	s_addc_u32 s11, s11, 0
	global_load_dwordx4 v[192:195], v1, s[10:11] nt
	global_load_dwordx4 v[196:199], v1, s[10:11] offset:1024 nt
	global_load_dwordx4 v[200:203], v1, s[10:11] offset:2048 nt
	global_load_dwordx4 v[204:207], v1, s[10:11] offset:3072 nt
	s_add_u32 s10, s10, 0x800000
	s_addc_u32 s11, s11, 0
	global_load_dwordx4 v[208:211], v1, s[10:11] nt
	global_load_dwordx4 v[212:215], v1, s[10:11] offset:1024 nt
	global_load_dwordx4 v[216:219], v1, s[10:11] offset:2048 nt
	global_load_dwordx4 v[220:223], v1, s[10:11] offset:3072 nt
	s_add_u32 s10, s10, 0x800000
	s_addc_u32 s11, s11, 0
	s_waitcnt vmcnt(16)
	v_cvt_pk_bf16_f32 v16, v40, v41
	v_cvt_pk_bf16_f32 v17, v42, v43
	v_cvt_pk_bf16_f32 v18, v44, v45
	v_cvt_pk_bf16_f32 v19, v46, v47
	v_cvt_pk_bf16_f32 v20, v48, v49
	v_cvt_pk_bf16_f32 v21, v50, v51
	v_cvt_pk_bf16_f32 v22, v52, v53
	v_cvt_pk_bf16_f32 v23, v54, v55
	v_mul_f32_e32 v8, v40, v40
	v_fmac_f32_e32 v8, v41, v41
	v_fmac_f32_e32 v8, v42, v42
	v_fmac_f32_e32 v8, v43, v43
	v_fmac_f32_e32 v8, v44, v44
	v_fmac_f32_e32 v8, v45, v45
	v_fmac_f32_e32 v8, v46, v46
	v_fmac_f32_e32 v8, v47, v47
	v_fmac_f32_e32 v8, v48, v48
	v_fmac_f32_e32 v8, v49, v49
	v_fmac_f32_e32 v8, v50, v50
	v_fmac_f32_e32 v8, v51, v51
	v_fmac_f32_e32 v8, v52, v52
	v_fmac_f32_e32 v8, v53, v53
	v_fmac_f32_e32 v8, v54, v54
	v_fmac_f32_e32 v8, v55, v55
	global_store_dwordx2 v2, v[16:17], s[12:13]
	global_store_dwordx2 v2, v[18:19], s[12:13] offset:512
	global_store_dwordx2 v2, v[20:21], s[12:13] offset:1024
	global_store_dwordx2 v2, v[22:23], s[12:13] offset:1536
	s_add_u32 s12, s12, 0x400000
	s_addc_u32 s13, s13, 0
	v_cvt_pk_bf16_f32 v24, v56, v57
	v_cvt_pk_bf16_f32 v25, v58, v59
	v_cvt_pk_bf16_f32 v26, v60, v61
	v_cvt_pk_bf16_f32 v27, v62, v63
	v_cvt_pk_bf16_f32 v28, v64, v65
	v_cvt_pk_bf16_f32 v29, v66, v67
	v_cvt_pk_bf16_f32 v30, v68, v69
	v_cvt_pk_bf16_f32 v31, v70, v71
	v_mul_f32_e32 v9, v56, v56
	v_fmac_f32_e32 v9, v57, v57
	v_fmac_f32_e32 v9, v58, v58
	v_fmac_f32_e32 v9, v59, v59
	v_fmac_f32_e32 v9, v60, v60
	v_fmac_f32_e32 v9, v61, v61
	v_fmac_f32_e32 v9, v62, v62
	v_fmac_f32_e32 v9, v63, v63
	v_fmac_f32_e32 v9, v64, v64
	v_fmac_f32_e32 v9, v65, v65
	v_fmac_f32_e32 v9, v66, v66
	v_fmac_f32_e32 v9, v67, v67
	v_fmac_f32_e32 v9, v68, v68
	v_fmac_f32_e32 v9, v69, v69
	v_fmac_f32_e32 v9, v70, v70
	v_fmac_f32_e32 v9, v71, v71
	global_store_dwordx2 v2, v[24:25], s[12:13]
	global_store_dwordx2 v2, v[26:27], s[12:13] offset:512
	global_store_dwordx2 v2, v[28:29], s[12:13] offset:1024
	global_store_dwordx2 v2, v[30:31], s[12:13] offset:1536
	s_add_u32 s12, s12, 0x400000
	s_addc_u32 s13, s13, 0
	v_cvt_pk_bf16_f32 v16, v72, v73
	v_cvt_pk_bf16_f32 v17, v74, v75
	v_cvt_pk_bf16_f32 v18, v76, v77
	v_cvt_pk_bf16_f32 v19, v78, v79
	v_cvt_pk_bf16_f32 v20, v80, v81
	v_cvt_pk_bf16_f32 v21, v82, v83
	v_cvt_pk_bf16_f32 v22, v84, v85
	v_cvt_pk_bf16_f32 v23, v86, v87
	v_mul_f32_e32 v10, v72, v72
	v_fmac_f32_e32 v10, v73, v73
	v_fmac_f32_e32 v10, v74, v74
	v_fmac_f32_e32 v10, v75, v75
	v_fmac_f32_e32 v10, v76, v76
	v_fmac_f32_e32 v10, v77, v77
	v_fmac_f32_e32 v10, v78, v78
	v_fmac_f32_e32 v10, v79, v79
	v_fmac_f32_e32 v10, v80, v80
; #define lane (hw_lane())
; __device__ __forceinline__ void prologue(const Args& a, LAS unsigned char* lds, int gw, int NGW, int lane, int wave) {
;     ...
;                 for (int j = 0; j < 4; ++j) nv[j] = __builtin_nontemporal_load(xr + 64 * j); } }
; #pragma unroll
;             for (int j = 0; j < 4; ++j) s += (v[j].x * v[j].x + v[j].y * v[j].y) + (v[j].z * v[j].z + v[j].w * v[j].w);
;             s = wave_sum(s);
;             float sc = 1.f;
;             if (is_mem) sc = __builtin_amdgcn_rsqf(s * (1.0f / D) + EPS);
;             else if (lane < 16) slots[(size_t)row * 16 + lane] = lane == 0 ? s : 0.f;
	v_fmac_f32_e32 v10, v81, v81
	v_fmac_f32_e32 v10, v82, v82
	v_fmac_f32_e32 v10, v83, v83
	v_fmac_f32_e32 v10, v84, v84
	v_fmac_f32_e32 v10, v85, v85
	v_fmac_f32_e32 v10, v86, v86
	v_fmac_f32_e32 v10, v87, v87
	global_store_dwordx2 v2, v[16:17], s[12:13]
	global_store_dwordx2 v2, v[18:19], s[12:13] offset:512
	global_store_dwordx2 v2, v[20:21], s[12:13] offset:1024
	global_store_dwordx2 v2, v[22:23], s[12:13] offset:1536
	s_add_u32 s12, s12, 0x400000
	s_addc_u32 s13, s13, 0
	v_cvt_pk_bf16_f32 v24, v88, v89
	v_cvt_pk_bf16_f32 v25, v90, v91
	v_cvt_pk_bf16_f32 v26, v92, v93
	v_cvt_pk_bf16_f32 v27, v94, v95
	v_cvt_pk_bf16_f32 v28, v96, v97
	v_cvt_pk_bf16_f32 v29, v98, v99
	v_cvt_pk_bf16_f32 v30, v100, v101
	v_cvt_pk_bf16_f32 v31, v102, v103
	v_mul_f32_e32 v11, v88, v88
	v_fmac_f32_e32 v11, v89, v89
	v_fmac_f32_e32 v11, v90, v90
	v_fmac_f32_e32 v11, v91, v91
	v_fmac_f32_e32 v11, v92, v92
	v_fmac_f32_e32 v11, v93, v93
	v_fmac_f32_e32 v11, v94, v94
	v_fmac_f32_e32 v11, v95, v95
	v_fmac_f32_e32 v11, v96, v96
	v_fmac_f32_e32 v11, v97, v97
	v_fmac_f32_e32 v11, v98, v98
	v_fmac_f32_e32 v11, v99, v99
	v_fmac_f32_e32 v11, v100, v100
	v_fmac_f32_e32 v11, v101, v101
	v_fmac_f32_e32 v11, v102, v102
	v_fmac_f32_e32 v11, v103, v103
	global_store_dwordx2 v2, v[24:25], s[12:13]
	global_store_dwordx2 v2, v[26:27], s[12:13] offset:512
	global_store_dwordx2 v2, v[28:29], s[12:13] offset:1024
	global_store_dwordx2 v2, v[30:31], s[12:13] offset:1536
	s_add_u32 s12, s12, 0x400000
	s_addc_u32 s13, s13, 0
	v_add_f32_dpp v12, v8, v8 row_ror:8 row_mask:0xf bank_mask:0xf
	v_add_f32_dpp v13, v9, v9 row_ror:8 row_mask:0xf bank_mask:0xf
	v_add_f32_dpp v14, v10, v10 row_ror:8 row_mask:0xf bank_mask:0xf
	v_add_f32_dpp v15, v11, v11 row_ror:8 row_mask:0xf bank_mask:0xf
	v_add_f32_dpp v8, v12, v12 row_ror:4 row_mask:0xf bank_mask:0xf
	v_add_f32_dpp v9, v13, v13 row_ror:4 row_mask:0xf bank_mask:0xf
	v_add_f32_dpp v10, v14, v14 row_ror:4 row_mask:0xf bank_mask:0xf
	v_add_f32_dpp v11, v15, v15 row_ror:4 row_mask:0xf bank_mask:0xf
	v_add_f32_dpp v12, v8, v8 row_ror:2 row_mask:0xf bank_mask:0xf
	v_add_f32_dpp v13, v9, v9 row_ror:2 row_mask:0xf bank_mask:0xf
	v_add_f32_dpp v14, v10, v10 row_ror:2 row_mask:0xf bank_mask:0xf
	v_add_f32_dpp v15, v11, v11 row_ror:2 row_mask:0xf bank_mask:0xf
	v_add_f32_dpp v8, v12, v12 row_ror:1 row_mask:0xf bank_mask:0xf
	v_add_f32_dpp v9, v13, v13 row_ror:1 row_mask:0xf bank_mask:0xf
	v_add_f32_dpp v10, v14, v14 row_ror:1 row_mask:0xf bank_mask:0xf
	v_add_f32_dpp v11, v15, v15 row_ror:1 row_mask:0xf bank_mask:0xf
	ds_bpermute_b32 v12, v4, v8
	ds_bpermute_b32 v13, v4, v9
	ds_bpermute_b32 v14, v4, v10
	ds_bpermute_b32 v15, v4, v11
	s_waitcnt lgkmcnt(0)
	v_add_f32_e32 v8, v8, v12
	v_add_f32_e32 v9, v9, v13
	v_add_f32_e32 v10, v10, v14
	v_add_f32_e32 v11, v11, v15
	ds_bpermute_b32 v12, v5, v8
	ds_bpermute_b32 v13, v5, v9
	ds_bpermute_b32 v14, v5, v10
	ds_bpermute_b32 v15, v5, v11
	s_waitcnt lgkmcnt(0)
	v_add_f32_e32 v8, v8, v12
	v_add_f32_e32 v9, v9, v13
	v_add_f32_e32 v10, v10, v14
	v_add_f32_e32 v11, v11, v15
	v_cndmask_b32_e64 v8, v6, v8, s[16:17]
	v_cndmask_b32_e64 v9, v6, v9, s[16:17]
	v_cndmask_b32_e64 v10, v6, v10, s[16:17]
	v_cndmask_b32_e64 v11, v6, v11, s[16:17]
	s_and_saveexec_b64 s[18:19], s[4:5]
	global_store_dword v3, v8, s[14:15]
	s_add_u32 s14, s14, 0x20000
	s_addc_u32 s15, s15, 0
	global_store_dword v3, v9, s[14:15]
	s_add_u32 s14, s14, 0x20000
	s_addc_u32 s15, s15, 0
	global_store_dword v3, v10, s[14:15]
	s_add_u32 s14, s14, 0x20000
	s_addc_u32 s15, s15, 0
	global_store_dword v3, v11, s[14:15]
	s_add_u32 s14, s14, 0x20000
	s_addc_u32 s15, s15, 0
	s_mov_b64 exec, s[18:19]
	global_load_dwordx4 v[40:43], v1, s[10:11] nt
	global_load_dwordx4 v[44:47], v1, s[10:11] offset:1024 nt
	global_load_dwordx4 v[48:51], v1, s[10:11] offset:2048 nt
	global_load_dwordx4 v[52:55], v1, s[10:11] offset:3072 nt
	s_add_u32 s10, s10, 0x800000
	s_addc_u32 s11, s11, 0
	global_load_dwordx4 v[56:59], v1, s[10:11] nt
	global_load_dwordx4 v[60:63], v1, s[10:11] offset:1024 nt
	global_load_dwordx4 v[64:67], v1, s[10:11] offset:2048 nt
	global_load_dwordx4 v[68:71], v1, s[10:11] offset:3072 nt
	s_add_u32 s10, s10, 0x800000
	s_addc_u32 s11, s11, 0
	global_load_dwordx4 v[72:75], v1, s[10:11] nt
	global_load_dwordx4 v[76:79], v1, s[10:11] offset:1024 nt
	global_load_dwordx4 v[80:83], v1, s[10:11] offset:2048 nt
	global_load_dwordx4 v[84:87], v1, s[10:11] offset:3072 nt
	s_add_u32 s10, s10, 0x800000
	s_addc_u32 s11, s11, 0
	global_load_dwordx4 v[88:91], v1, s[10:11] nt
	global_load_dwordx4 v[92:95], v1, s[10:11] offset:1024 nt
	global_load_dwordx4 v[96:99], v1, s[10:11] offset:2048 nt
	global_load_dwordx4 v[100:103], v1, s[10:11] offset:3072 nt
	s_add_u32 s10, s10, 0x800000
	s_addc_u32 s11, s11, 0
	s_waitcnt vmcnt(36)
; __device__ __forceinline__ unsigned pk2(float lo, float hi) { return f2bf(lo) | (f2bf(hi) << 16); }
; #define lane (hw_lane())
; __device__ __forceinline__ void prologue(const Args& a, LAS unsigned char* lds, int gw, int NGW, int lane, int wave) {
;     ...
;             for (int j = 0; j < 4; ++j) s += (v[j].x * v[j].x + v[j].y * v[j].y) + (v[j].z * v[j].z + v[j].w * v[j].w);
;             s = wave_sum(s);
;             float sc = 1.f;
;             if (is_mem) sc = __builtin_amdgcn_rsqf(s * (1.0f / D) + EPS);
;             else if (lane < 16) slots[(size_t)row * 16 + lane] = lane == 0 ? s : 0.f;
;             v2u* o8 = (v2u*)((is_mem ? MEMN : HB) + (size_t)row * D) + lane;
; #pragma unroll
;             for (int j = 0; j < 4; ++j) { v2u o; o.x = pk2(v[j].x * sc, v[j].y * sc); o.y = pk2(v[j].z * sc, v[j].w * sc); o8[64 * j] = o; }
	v_cvt_pk_bf16_f32 v16, v160, v161
	v_cvt_pk_bf16_f32 v17, v162, v163
	v_cvt_pk_bf16_f32 v18, v164, v165
	v_cvt_pk_bf16_f32 v19, v166, v167
	v_cvt_pk_bf16_f32 v20, v168, v169
	v_cvt_pk_bf16_f32 v21, v170, v171
	v_cvt_pk_bf16_f32 v22, v172, v173
	v_cvt_pk_bf16_f32 v23, v174, v175
	v_mul_f32_e32 v8, v160, v160
	v_fmac_f32_e32 v8, v161, v161
	v_fmac_f32_e32 v8, v162, v162
	v_fmac_f32_e32 v8, v163, v163
	v_fmac_f32_e32 v8, v164, v164
	v_fmac_f32_e32 v8, v165, v165
	v_fmac_f32_e32 v8, v166, v166
	v_fmac_f32_e32 v8, v167, v167
	v_fmac_f32_e32 v8, v168, v168
	v_fmac_f32_e32 v8, v169, v169
	v_fmac_f32_e32 v8, v170, v170
	v_fmac_f32_e32 v8, v171, v171
	v_fmac_f32_e32 v8, v172, v172
	v_fmac_f32_e32 v8, v173, v173
	v_fmac_f32_e32 v8, v174, v174
	v_fmac_f32_e32 v8, v175, v175
	global_store_dwordx2 v2, v[16:17], s[12:13]
	global_store_dwordx2 v2, v[18:19], s[12:13] offset:512
	global_store_dwordx2 v2, v[20:21], s[12:13] offset:1024
	global_store_dwordx2 v2, v[22:23], s[12:13] offset:1536
	s_add_u32 s12, s12, 0x400000
	s_addc_u32 s13, s13, 0
	v_cvt_pk_bf16_f32 v24, v176, v177
	v_cvt_pk_bf16_f32 v25, v178, v179
	v_cvt_pk_bf16_f32 v26, v180, v181
	v_cvt_pk_bf16_f32 v27, v182, v183
	v_cvt_pk_bf16_f32 v28, v184, v185
	v_cvt_pk_bf16_f32 v29, v186, v187
	v_cvt_pk_bf16_f32 v30, v188, v189
	v_cvt_pk_bf16_f32 v31, v190, v191
	v_mul_f32_e32 v9, v176, v176
	v_fmac_f32_e32 v9, v177, v177
	v_fmac_f32_e32 v9, v178, v178
	v_fmac_f32_e32 v9, v179, v179
	v_fmac_f32_e32 v9, v180, v180
	v_fmac_f32_e32 v9, v181, v181
	v_fmac_f32_e32 v9, v182, v182
	v_fmac_f32_e32 v9, v183, v183
	v_fmac_f32_e32 v9, v184, v184
	v_fmac_f32_e32 v9, v185, v185
	v_fmac_f32_e32 v9, v186, v186
	v_fmac_f32_e32 v9, v187, v187
	v_fmac_f32_e32 v9, v188, v188
	v_fmac_f32_e32 v9, v189, v189
	v_fmac_f32_e32 v9, v190, v190
	v_fmac_f32_e32 v9, v191, v191
	global_store_dwordx2 v2, v[24:25], s[12:13]
	global_store_dwordx2 v2, v[26:27], s[12:13] offset:512
	global_store_dwordx2 v2, v[28:29], s[12:13] offset:1024
	global_store_dwordx2 v2, v[30:31], s[12:13] offset:1536
	s_add_u32 s12, s12, 0x400000
	s_addc_u32 s13, s13, 0
	v_cvt_pk_bf16_f32 v16, v192, v193
	v_cvt_pk_bf16_f32 v17, v194, v195
	v_cvt_pk_bf16_f32 v18, v196, v197
	v_cvt_pk_bf16_f32 v19, v198, v199
	v_cvt_pk_bf16_f32 v20, v200, v201
	v_cvt_pk_bf16_f32 v21, v202, v203
	v_cvt_pk_bf16_f32 v22, v204, v205
	v_cvt_pk_bf16_f32 v23, v206, v207
	v_mul_f32_e32 v10, v192, v192
	v_fmac_f32_e32 v10, v193, v193
	v_fmac_f32_e32 v10, v194, v194
	v_fmac_f32_e32 v10, v195, v195
	v_fmac_f32_e32 v10, v196, v196
	v_fmac_f32_e32 v10, v197, v197
	v_fmac_f32_e32 v10, v198, v198
	v_fmac_f32_e32 v10, v199, v199
	v_fmac_f32_e32 v10, v200, v200
	v_fmac_f32_e32 v10, v201, v201
	v_fmac_f32_e32 v10, v202, v202
	v_fmac_f32_e32 v10, v203, v203
	v_fmac_f32_e32 v10, v204, v204
	v_fmac_f32_e32 v10, v205, v205
	v_fmac_f32_e32 v10, v206, v206
	v_fmac_f32_e32 v10, v207, v207
	global_store_dwordx2 v2, v[16:17], s[12:13]
	global_store_dwordx2 v2, v[18:19], s[12:13] offset:512
	global_store_dwordx2 v2, v[20:21], s[12:13] offset:1024
	global_store_dwordx2 v2, v[22:23], s[12:13] offset:1536
	s_add_u32 s12, s12, 0x400000
	s_addc_u32 s13, s13, 0
	v_cvt_pk_bf16_f32 v24, v208, v209
	v_cvt_pk_bf16_f32 v25, v210, v211
	v_cvt_pk_bf16_f32 v26, v212, v213
	v_cvt_pk_bf16_f32 v27, v214, v215
	v_cvt_pk_bf16_f32 v28, v216, v217
	v_cvt_pk_bf16_f32 v29, v218, v219
	v_cvt_pk_bf16_f32 v30, v220, v221
	v_cvt_pk_bf16_f32 v31, v222, v223
	v_mul_f32_e32 v11, v208, v208
	v_fmac_f32_e32 v11, v209, v209
	v_fmac_f32_e32 v11, v210, v210
	v_fmac_f32_e32 v11, v211, v211
	v_fmac_f32_e32 v11, v212, v212
	v_fmac_f32_e32 v11, v213, v213
	v_fmac_f32_e32 v11, v214, v214
	v_fmac_f32_e32 v11, v215, v215
	v_fmac_f32_e32 v11, v216, v216
	v_fmac_f32_e32 v11, v217, v217
	v_fmac_f32_e32 v11, v218, v218
	v_fmac_f32_e32 v11, v219, v219
	v_fmac_f32_e32 v11, v220, v220
	v_fmac_f32_e32 v11, v221, v221
	v_fmac_f32_e32 v11, v222, v222
	v_fmac_f32_e32 v11, v223, v223
	global_store_dwordx2 v2, v[24:25], s[12:13]
	global_store_dwordx2 v2, v[26:27], s[12:13] offset:512
	global_store_dwordx2 v2, v[28:29], s[12:13] offset:1024
	global_store_dwordx2 v2, v[30:31], s[12:13] offset:1536
	s_add_u32 s12, s12, 0x400000
	s_addc_u32 s13, s13, 0
	v_add_f32_dpp v12, v8, v8 row_ror:8 row_mask:0xf bank_mask:0xf
	v_add_f32_dpp v13, v9, v9 row_ror:8 row_mask:0xf bank_mask:0xf
	v_add_f32_dpp v14, v10, v10 row_ror:8 row_mask:0xf bank_mask:0xf
	v_add_f32_dpp v15, v11, v11 row_ror:8 row_mask:0xf bank_mask:0xf
	v_add_f32_dpp v8, v12, v12 row_ror:4 row_mask:0xf bank_mask:0xf
	v_add_f32_dpp v9, v13, v13 row_ror:4 row_mask:0xf bank_mask:0xf
	v_add_f32_dpp v10, v14, v14 row_ror:4 row_mask:0xf bank_mask:0xf
	v_add_f32_dpp v11, v15, v15 row_ror:4 row_mask:0xf bank_mask:0xf
	v_add_f32_dpp v12, v8, v8 row_ror:2 row_mask:0xf bank_mask:0xf
	v_add_f32_dpp v13, v9, v9 row_ror:2 row_mask:0xf bank_mask:0xf
	v_add_f32_dpp v14, v10, v10 row_ror:2 row_mask:0xf bank_mask:0xf
	v_add_f32_dpp v15, v11, v11 row_ror:2 row_mask:0xf bank_mask:0xf
	v_add_f32_dpp v8, v12, v12 row_ror:1 row_mask:0xf bank_mask:0xf
	v_add_f32_dpp v9, v13, v13 row_ror:1 row_mask:0xf bank_mask:0xf
	v_add_f32_dpp v10, v14, v14 row_ror:1 row_mask:0xf bank_mask:0xf
	v_add_f32_dpp v11, v15, v15 row_ror:1 row_mask:0xf bank_mask:0xf
	ds_bpermute_b32 v12, v4, v8
	ds_bpermute_b32 v13, v4, v9
	ds_bpermute_b32 v14, v4, v10
	ds_bpermute_b32 v15, v4, v11
	s_waitcnt lgkmcnt(0)
	v_add_f32_e32 v8, v8, v12
	v_add_f32_e32 v9, v9, v13
	v_add_f32_e32 v10, v10, v14
	v_add_f32_e32 v11, v11, v15
	ds_bpermute_b32 v12, v5, v8
	ds_bpermute_b32 v13, v5, v9
	ds_bpermute_b32 v14, v5, v10
	ds_bpermute_b32 v15, v5, v11
	s_waitcnt lgkmcnt(0)
; __device__ __forceinline__ unsigned pk2(float lo, float hi) { return f2bf(lo) | (f2bf(hi) << 16); }
; #define lane (hw_lane())
; __device__ __forceinline__ void prologue(const Args& a, LAS unsigned char* lds, int gw, int NGW, int lane, int wave) {
;     ...
;                 for (int j = 0; j < 4; ++j) nv[j] = __builtin_nontemporal_load(xr + 64 * j); } }
; #pragma unroll
;             for (int j = 0; j < 4; ++j) s += (v[j].x * v[j].x + v[j].y * v[j].y) + (v[j].z * v[j].z + v[j].w * v[j].w);
;             s = wave_sum(s);
;             float sc = 1.f;
;             if (is_mem) sc = __builtin_amdgcn_rsqf(s * (1.0f / D) + EPS);
;             else if (lane < 16) slots[(size_t)row * 16 + lane] = lane == 0 ? s : 0.f;
;             v2u* o8 = (v2u*)((is_mem ? MEMN : HB) + (size_t)row * D) + lane;
; #pragma unroll
;             for (int j = 0; j < 4; ++j) { v2u o; o.x = pk2(v[j].x * sc, v[j].y * sc); o.y = pk2(v[j].z * sc, v[j].w * sc); o8[64 * j] = o; }
	v_add_f32_e32 v8, v8, v12
	v_add_f32_e32 v9, v9, v13
	v_add_f32_e32 v10, v10, v14
	v_add_f32_e32 v11, v11, v15
	v_cndmask_b32_e64 v8, v6, v8, s[16:17]
	v_cndmask_b32_e64 v9, v6, v9, s[16:17]
	v_cndmask_b32_e64 v10, v6, v10, s[16:17]
	v_cndmask_b32_e64 v11, v6, v11, s[16:17]
	s_and_saveexec_b64 s[18:19], s[4:5]
	global_store_dword v3, v8, s[14:15]
	s_add_u32 s14, s14, 0x20000
	s_addc_u32 s15, s15, 0
	global_store_dword v3, v9, s[14:15]
	s_add_u32 s14, s14, 0x20000
	s_addc_u32 s15, s15, 0
	global_store_dword v3, v10, s[14:15]
	s_add_u32 s14, s14, 0x20000
	s_addc_u32 s15, s15, 0
	global_store_dword v3, v11, s[14:15]
	s_add_u32 s14, s14, 0x20000
	s_addc_u32 s15, s15, 0
	s_mov_b64 exec, s[18:19]
	global_load_dwordx4 v[160:163], v1, s[10:11] nt
	global_load_dwordx4 v[164:167], v1, s[10:11] offset:1024 nt
	global_load_dwordx4 v[168:171], v1, s[10:11] offset:2048 nt
	global_load_dwordx4 v[172:175], v1, s[10:11] offset:3072 nt
	s_add_u32 s10, s10, 0x800000
	s_addc_u32 s11, s11, 0
	global_load_dwordx4 v[176:179], v1, s[10:11] nt
	global_load_dwordx4 v[180:183], v1, s[10:11] offset:1024 nt
	global_load_dwordx4 v[184:187], v1, s[10:11] offset:2048 nt
	global_load_dwordx4 v[188:191], v1, s[10:11] offset:3072 nt
	s_add_u32 s10, s10, 0x800000
	s_addc_u32 s11, s11, 0
	global_load_dwordx4 v[192:195], v1, s[10:11] nt
	global_load_dwordx4 v[196:199], v1, s[10:11] offset:1024 nt
	global_load_dwordx4 v[200:203], v1, s[10:11] offset:2048 nt
	global_load_dwordx4 v[204:207], v1, s[10:11] offset:3072 nt
	s_add_u32 s10, s10, 0x800000
	s_addc_u32 s11, s11, 0
	global_load_dwordx4 v[208:211], v1, s[10:11] nt
	global_load_dwordx4 v[212:215], v1, s[10:11] offset:1024 nt
	global_load_dwordx4 v[216:219], v1, s[10:11] offset:2048 nt
	global_load_dwordx4 v[220:223], v1, s[10:11] offset:3072 nt
	s_add_u32 s10, s10, 0x800000
	s_addc_u32 s11, s11, 0
	s_waitcnt vmcnt(36)
	v_cvt_pk_bf16_f32 v16, v40, v41
	v_cvt_pk_bf16_f32 v17, v42, v43
	v_cvt_pk_bf16_f32 v18, v44, v45
	v_cvt_pk_bf16_f32 v19, v46, v47
	v_cvt_pk_bf16_f32 v20, v48, v49
	v_cvt_pk_bf16_f32 v21, v50, v51
	v_cvt_pk_bf16_f32 v22, v52, v53
	v_cvt_pk_bf16_f32 v23, v54, v55
	v_mul_f32_e32 v8, v40, v40
	v_fmac_f32_e32 v8, v41, v41
	v_fmac_f32_e32 v8, v42, v42
	v_fmac_f32_e32 v8, v43, v43
	v_fmac_f32_e32 v8, v44, v44
	v_fmac_f32_e32 v8, v45, v45
	v_fmac_f32_e32 v8, v46, v46
	v_fmac_f32_e32 v8, v47, v47
	v_fmac_f32_e32 v8, v48, v48
	v_fmac_f32_e32 v8, v49, v49
	v_fmac_f32_e32 v8, v50, v50
	v_fmac_f32_e32 v8, v51, v51
	v_fmac_f32_e32 v8, v52, v52
	v_fmac_f32_e32 v8, v53, v53
	v_fmac_f32_e32 v8, v54, v54
	v_fmac_f32_e32 v8, v55, v55
	global_store_dwordx2 v2, v[16:17], s[12:13]
	global_store_dwordx2 v2, v[18:19], s[12:13] offset:512
	global_store_dwordx2 v2, v[20:21], s[12:13] offset:1024
	global_store_dwordx2 v2, v[22:23], s[12:13] offset:1536
	s_add_u32 s12, s12, 0x400000
	s_addc_u32 s13, s13, 0
	v_cvt_pk_bf16_f32 v24, v56, v57
	v_cvt_pk_bf16_f32 v25, v58, v59
	v_cvt_pk_bf16_f32 v26, v60, v61
	v_cvt_pk_bf16_f32 v27, v62, v63
	v_cvt_pk_bf16_f32 v28, v64, v65
	v_cvt_pk_bf16_f32 v29, v66, v67
	v_cvt_pk_bf16_f32 v30, v68, v69
	v_cvt_pk_bf16_f32 v31, v70, v71
	v_mul_f32_e32 v9, v56, v56
	v_fmac_f32_e32 v9, v57, v57
	v_fmac_f32_e32 v9, v58, v58
	v_fmac_f32_e32 v9, v59, v59
	v_fmac_f32_e32 v9, v60, v60
	v_fmac_f32_e32 v9, v61, v61
	v_fmac_f32_e32 v9, v62, v62
	v_fmac_f32_e32 v9, v63, v63
	v_fmac_f32_e32 v9, v64, v64
	v_fmac_f32_e32 v9, v65, v65
	v_fmac_f32_e32 v9, v66, v66
	v_fmac_f32_e32 v9, v67, v67
	v_fmac_f32_e32 v9, v68, v68
	v_fmac_f32_e32 v9, v69, v69
	v_fmac_f32_e32 v9, v70, v70
	v_fmac_f32_e32 v9, v71, v71
	global_store_dwordx2 v2, v[24:25], s[12:13]
	global_store_dwordx2 v2, v[26:27], s[12:13] offset:512
	global_store_dwordx2 v2, v[28:29], s[12:13] offset:1024
	global_store_dwordx2 v2, v[30:31], s[12:13] offset:1536
	s_add_u32 s12, s12, 0x400000
	s_addc_u32 s13, s13, 0
	v_cvt_pk_bf16_f32 v16, v72, v73
	v_cvt_pk_bf16_f32 v17, v74, v75
	v_cvt_pk_bf16_f32 v18, v76, v77
	v_cvt_pk_bf16_f32 v19, v78, v79
	v_cvt_pk_bf16_f32 v20, v80, v81
	v_cvt_pk_bf16_f32 v21, v82, v83
	v_cvt_pk_bf16_f32 v22, v84, v85
	v_cvt_pk_bf16_f32 v23, v86, v87
	v_mul_f32_e32 v10, v72, v72
	v_fmac_f32_e32 v10, v73, v73
	v_fmac_f32_e32 v10, v74, v74
	v_fmac_f32_e32 v10, v75, v75
	v_fmac_f32_e32 v10, v76, v76
	v_fmac_f32_e32 v10, v77, v77
	v_fmac_f32_e32 v10, v78, v78
	v_fmac_f32_e32 v10, v79, v79
	v_fmac_f32_e32 v10, v80, v80
	v_fmac_f32_e32 v10, v81, v81
	v_fmac_f32_e32 v10, v82, v82
	v_fmac_f32_e32 v10, v83, v83
	v_fmac_f32_e32 v10, v84, v84
	v_fmac_f32_e32 v10, v85, v85
	v_fmac_f32_e32 v10, v86, v86
	v_fmac_f32_e32 v10, v87, v87
	global_store_dwordx2 v2, v[16:17], s[12:13]
	global_store_dwordx2 v2, v[18:19], s[12:13] offset:512
	global_store_dwordx2 v2, v[20:21], s[12:13] offset:1024
	global_store_dwordx2 v2, v[22:23], s[12:13] offset:1536
	s_add_u32 s12, s12, 0x400000
	s_addc_u32 s13, s13, 0
	v_cvt_pk_bf16_f32 v24, v88, v89
	v_cvt_pk_bf16_f32 v25, v90, v91
	v_cvt_pk_bf16_f32 v26, v92, v93
	v_cvt_pk_bf16_f32 v27, v94, v95
	v_cvt_pk_bf16_f32 v28, v96, v97
	v_cvt_pk_bf16_f32 v29, v98, v99
	v_cvt_pk_bf16_f32 v30, v100, v101
	v_cvt_pk_bf16_f32 v31, v102, v103
	v_mul_f32_e32 v11, v88, v88
	v_fmac_f32_e32 v11, v89, v89
	v_fmac_f32_e32 v11, v90, v90
	v_fmac_f32_e32 v11, v91, v91
	v_fmac_f32_e32 v11, v92, v92
	v_fmac_f32_e32 v11, v93, v93
	v_fmac_f32_e32 v11, v94, v94
	v_fmac_f32_e32 v11, v95, v95
	v_fmac_f32_e32 v11, v96, v96
	v_fmac_f32_e32 v11, v97, v97
	v_fmac_f32_e32 v11, v98, v98
	v_fmac_f32_e32 v11, v99, v99
	v_fmac_f32_e32 v11, v100, v100
	v_fmac_f32_e32 v11, v101, v101
	v_fmac_f32_e32 v11, v102, v102
	v_fmac_f32_e32 v11, v103, v103
; __device__ __forceinline__ unsigned pk2(float lo, float hi) { return f2bf(lo) | (f2bf(hi) << 16); }
; #define lane (hw_lane())
; __device__ __forceinline__ void prologue(const Args& a, LAS unsigned char* lds, int gw, int NGW, int lane, int wave) {
;     ...
;                 for (int j = 0; j < 4; ++j) nv[j] = __builtin_nontemporal_load(xr + 64 * j); } }
; #pragma unroll
;             for (int j = 0; j < 4; ++j) s += (v[j].x * v[j].x + v[j].y * v[j].y) + (v[j].z * v[j].z + v[j].w * v[j].w);
;             s = wave_sum(s);
;             float sc = 1.f;
;             if (is_mem) sc = __builtin_amdgcn_rsqf(s * (1.0f / D) + EPS);
;             else if (lane < 16) slots[(size_t)row * 16 + lane] = lane == 0 ? s : 0.f;
;             v2u* o8 = (v2u*)((is_mem ? MEMN : HB) + (size_t)row * D) + lane;
; #pragma unroll
;             for (int j = 0; j < 4; ++j) { v2u o; o.x = pk2(v[j].x * sc, v[j].y * sc); o.y = pk2(v[j].z * sc, v[j].w * sc); o8[64 * j] = o; }
	global_store_dwordx2 v2, v[24:25], s[12:13]
	global_store_dwordx2 v2, v[26:27], s[12:13] offset:512
	global_store_dwordx2 v2, v[28:29], s[12:13] offset:1024
	global_store_dwordx2 v2, v[30:31], s[12:13] offset:1536
	s_add_u32 s12, s12, 0x400000
	s_addc_u32 s13, s13, 0
	v_add_f32_dpp v12, v8, v8 row_ror:8 row_mask:0xf bank_mask:0xf
	v_add_f32_dpp v13, v9, v9 row_ror:8 row_mask:0xf bank_mask:0xf
	v_add_f32_dpp v14, v10, v10 row_ror:8 row_mask:0xf bank_mask:0xf
	v_add_f32_dpp v15, v11, v11 row_ror:8 row_mask:0xf bank_mask:0xf
	v_add_f32_dpp v8, v12, v12 row_ror:4 row_mask:0xf bank_mask:0xf
	v_add_f32_dpp v9, v13, v13 row_ror:4 row_mask:0xf bank_mask:0xf
	v_add_f32_dpp v10, v14, v14 row_ror:4 row_mask:0xf bank_mask:0xf
	v_add_f32_dpp v11, v15, v15 row_ror:4 row_mask:0xf bank_mask:0xf
	v_add_f32_dpp v12, v8, v8 row_ror:2 row_mask:0xf bank_mask:0xf
	v_add_f32_dpp v13, v9, v9 row_ror:2 row_mask:0xf bank_mask:0xf
	v_add_f32_dpp v14, v10, v10 row_ror:2 row_mask:0xf bank_mask:0xf
	v_add_f32_dpp v15, v11, v11 row_ror:2 row_mask:0xf bank_mask:0xf
	v_add_f32_dpp v8, v12, v12 row_ror:1 row_mask:0xf bank_mask:0xf
	v_add_f32_dpp v9, v13, v13 row_ror:1 row_mask:0xf bank_mask:0xf
	v_add_f32_dpp v10, v14, v14 row_ror:1 row_mask:0xf bank_mask:0xf
	v_add_f32_dpp v11, v15, v15 row_ror:1 row_mask:0xf bank_mask:0xf
	ds_bpermute_b32 v12, v4, v8
	ds_bpermute_b32 v13, v4, v9
	ds_bpermute_b32 v14, v4, v10
	ds_bpermute_b32 v15, v4, v11
	s_waitcnt lgkmcnt(0)
	v_add_f32_e32 v8, v8, v12
	v_add_f32_e32 v9, v9, v13
	v_add_f32_e32 v10, v10, v14
	v_add_f32_e32 v11, v11, v15
	ds_bpermute_b32 v12, v5, v8
	ds_bpermute_b32 v13, v5, v9
	ds_bpermute_b32 v14, v5, v10
	ds_bpermute_b32 v15, v5, v11
	s_waitcnt lgkmcnt(0)
	v_add_f32_e32 v8, v8, v12
	v_add_f32_e32 v9, v9, v13
	v_add_f32_e32 v10, v10, v14
	v_add_f32_e32 v11, v11, v15
	v_cndmask_b32_e64 v8, v6, v8, s[16:17]
	v_cndmask_b32_e64 v9, v6, v9, s[16:17]
	v_cndmask_b32_e64 v10, v6, v10, s[16:17]
	v_cndmask_b32_e64 v11, v6, v11, s[16:17]
	s_and_saveexec_b64 s[18:19], s[4:5]
	global_store_dword v3, v8, s[14:15]
	s_add_u32 s14, s14, 0x20000
	s_addc_u32 s15, s15, 0
	global_store_dword v3, v9, s[14:15]
	s_add_u32 s14, s14, 0x20000
	s_addc_u32 s15, s15, 0
	global_store_dword v3, v10, s[14:15]
	s_add_u32 s14, s14, 0x20000
	s_addc_u32 s15, s15, 0
	global_store_dword v3, v11, s[14:15]
	s_add_u32 s14, s14, 0x20000
	s_addc_u32 s15, s15, 0
	s_mov_b64 exec, s[18:19]
	global_load_dwordx4 v[40:43], v1, s[10:11] nt
	global_load_dwordx4 v[44:47], v1, s[10:11] offset:1024 nt
	global_load_dwordx4 v[48:51], v1, s[10:11] offset:2048 nt
	global_load_dwordx4 v[52:55], v1, s[10:11] offset:3072 nt
	s_add_u32 s10, s10, 0x800000
	s_addc_u32 s11, s11, 0
	global_load_dwordx4 v[56:59], v1, s[10:11] nt
	global_load_dwordx4 v[60:63], v1, s[10:11] offset:1024 nt
	global_load_dwordx4 v[64:67], v1, s[10:11] offset:2048 nt
	global_load_dwordx4 v[68:71], v1, s[10:11] offset:3072 nt
	s_add_u32 s10, s10, 0x800000
	s_addc_u32 s11, s11, 0
	global_load_dwordx4 v[72:75], v1, s[10:11] nt
	global_load_dwordx4 v[76:79], v1, s[10:11] offset:1024 nt
	global_load_dwordx4 v[80:83], v1, s[10:11] offset:2048 nt
	global_load_dwordx4 v[84:87], v1, s[10:11] offset:3072 nt
	s_add_u32 s10, s10, 0x800000
	s_addc_u32 s11, s11, 0
	global_load_dwordx4 v[88:91], v1, s[10:11] nt
	global_load_dwordx4 v[92:95], v1, s[10:11] offset:1024 nt
	global_load_dwordx4 v[96:99], v1, s[10:11] offset:2048 nt
	global_load_dwordx4 v[100:103], v1, s[10:11] offset:3072 nt
	s_add_u32 s10, s10, 0x800000
	s_addc_u32 s11, s11, 0
	s_waitcnt vmcnt(36)
	v_cvt_pk_bf16_f32 v16, v160, v161
	v_cvt_pk_bf16_f32 v17, v162, v163
	v_cvt_pk_bf16_f32 v18, v164, v165
	v_cvt_pk_bf16_f32 v19, v166, v167
	v_cvt_pk_bf16_f32 v20, v168, v169
	v_cvt_pk_bf16_f32 v21, v170, v171
	v_cvt_pk_bf16_f32 v22, v172, v173
	v_cvt_pk_bf16_f32 v23, v174, v175
	v_mul_f32_e32 v8, v160, v160
	v_fmac_f32_e32 v8, v161, v161
	v_fmac_f32_e32 v8, v162, v162
	v_fmac_f32_e32 v8, v163, v163
	v_fmac_f32_e32 v8, v164, v164
	v_fmac_f32_e32 v8, v165, v165
	v_fmac_f32_e32 v8, v166, v166
	v_fmac_f32_e32 v8, v167, v167
	v_fmac_f32_e32 v8, v168, v168
	v_fmac_f32_e32 v8, v169, v169
	v_fmac_f32_e32 v8, v170, v170
	v_fmac_f32_e32 v8, v171, v171
	v_fmac_f32_e32 v8, v172, v172
	v_fmac_f32_e32 v8, v173, v173
	v_fmac_f32_e32 v8, v174, v174
	v_fmac_f32_e32 v8, v175, v175
	global_store_dwordx2 v2, v[16:17], s[12:13]
	global_store_dwordx2 v2, v[18:19], s[12:13] offset:512
	global_store_dwordx2 v2, v[20:21], s[12:13] offset:1024
	global_store_dwordx2 v2, v[22:23], s[12:13] offset:1536
	s_add_u32 s12, s12, 0x400000
	s_addc_u32 s13, s13, 0
	v_cvt_pk_bf16_f32 v24, v176, v177
	v_cvt_pk_bf16_f32 v25, v178, v179
	v_cvt_pk_bf16_f32 v26, v180, v181
	v_cvt_pk_bf16_f32 v27, v182, v183
	v_cvt_pk_bf16_f32 v28, v184, v185
	v_cvt_pk_bf16_f32 v29, v186, v187
	v_cvt_pk_bf16_f32 v30, v188, v189
	v_cvt_pk_bf16_f32 v31, v190, v191
	v_mul_f32_e32 v9, v176, v176
	v_fmac_f32_e32 v9, v177, v177
	v_fmac_f32_e32 v9, v178, v178
	v_fmac_f32_e32 v9, v179, v179
	v_fmac_f32_e32 v9, v180, v180
	v_fmac_f32_e32 v9, v181, v181
	v_fmac_f32_e32 v9, v182, v182
	v_fmac_f32_e32 v9, v183, v183
	v_fmac_f32_e32 v9, v184, v184
	v_fmac_f32_e32 v9, v185, v185
	v_fmac_f32_e32 v9, v186, v186
	v_fmac_f32_e32 v9, v187, v187
	v_fmac_f32_e32 v9, v188, v188
	v_fmac_f32_e32 v9, v189, v189
	v_fmac_f32_e32 v9, v190, v190
	v_fmac_f32_e32 v9, v191, v191
	global_store_dwordx2 v2, v[24:25], s[12:13]
	global_store_dwordx2 v2, v[26:27], s[12:13] offset:512
	global_store_dwordx2 v2, v[28:29], s[12:13] offset:1024
	global_store_dwordx2 v2, v[30:31], s[12:13] offset:1536
	s_add_u32 s12, s12, 0x400000
	s_addc_u32 s13, s13, 0
; __device__ __forceinline__ unsigned pk2(float lo, float hi) { return f2bf(lo) | (f2bf(hi) << 16); }
; #define lane (hw_lane())
; __device__ __forceinline__ void prologue(const Args& a, LAS unsigned char* lds, int gw, int NGW, int lane, int wave) {
;     ...
;                 for (int j = 0; j < 4; ++j) nv[j] = __builtin_nontemporal_load(xr + 64 * j); } }
; #pragma unroll
;             for (int j = 0; j < 4; ++j) s += (v[j].x * v[j].x + v[j].y * v[j].y) + (v[j].z * v[j].z + v[j].w * v[j].w);
;             s = wave_sum(s);
;             float sc = 1.f;
;             if (is_mem) sc = __builtin_amdgcn_rsqf(s * (1.0f / D) + EPS);
;             else if (lane < 16) slots[(size_t)row * 16 + lane] = lane == 0 ? s : 0.f;
;             v2u* o8 = (v2u*)((is_mem ? MEMN : HB) + (size_t)row * D) + lane;
; #pragma unroll
;             for (int j = 0; j < 4; ++j) { v2u o; o.x = pk2(v[j].x * sc, v[j].y * sc); o.y = pk2(v[j].z * sc, v[j].w * sc); o8[64 * j] = o; }
	v_cvt_pk_bf16_f32 v16, v192, v193
	v_cvt_pk_bf16_f32 v17, v194, v195
	v_cvt_pk_bf16_f32 v18, v196, v197
	v_cvt_pk_bf16_f32 v19, v198, v199
	v_cvt_pk_bf16_f32 v20, v200, v201
	v_cvt_pk_bf16_f32 v21, v202, v203
	v_cvt_pk_bf16_f32 v22, v204, v205
	v_cvt_pk_bf16_f32 v23, v206, v207
	v_mul_f32_e32 v10, v192, v192
	v_fmac_f32_e32 v10, v193, v193
	v_fmac_f32_e32 v10, v194, v194
	v_fmac_f32_e32 v10, v195, v195
	v_fmac_f32_e32 v10, v196, v196
	v_fmac_f32_e32 v10, v197, v197
	v_fmac_f32_e32 v10, v198, v198
	v_fmac_f32_e32 v10, v199, v199
	v_fmac_f32_e32 v10, v200, v200
	v_fmac_f32_e32 v10, v201, v201
	v_fmac_f32_e32 v10, v202, v202
	v_fmac_f32_e32 v10, v203, v203
	v_fmac_f32_e32 v10, v204, v204
	v_fmac_f32_e32 v10, v205, v205
	v_fmac_f32_e32 v10, v206, v206
	v_fmac_f32_e32 v10, v207, v207
	global_store_dwordx2 v2, v[16:17], s[12:13]
	global_store_dwordx2 v2, v[18:19], s[12:13] offset:512
	global_store_dwordx2 v2, v[20:21], s[12:13] offset:1024
	global_store_dwordx2 v2, v[22:23], s[12:13] offset:1536
	s_add_u32 s12, s12, 0x400000
	s_addc_u32 s13, s13, 0
	v_cvt_pk_bf16_f32 v24, v208, v209
	v_cvt_pk_bf16_f32 v25, v210, v211
	v_cvt_pk_bf16_f32 v26, v212, v213
	v_cvt_pk_bf16_f32 v27, v214, v215
	v_cvt_pk_bf16_f32 v28, v216, v217
	v_cvt_pk_bf16_f32 v29, v218, v219
	v_cvt_pk_bf16_f32 v30, v220, v221
	v_cvt_pk_bf16_f32 v31, v222, v223
	v_mul_f32_e32 v11, v208, v208
	v_fmac_f32_e32 v11, v209, v209
	v_fmac_f32_e32 v11, v210, v210
	v_fmac_f32_e32 v11, v211, v211
	v_fmac_f32_e32 v11, v212, v212
	v_fmac_f32_e32 v11, v213, v213
	v_fmac_f32_e32 v11, v214, v214
	v_fmac_f32_e32 v11, v215, v215
	v_fmac_f32_e32 v11, v216, v216
	v_fmac_f32_e32 v11, v217, v217
	v_fmac_f32_e32 v11, v218, v218
	v_fmac_f32_e32 v11, v219, v219
	v_fmac_f32_e32 v11, v220, v220
	v_fmac_f32_e32 v11, v221, v221
	v_fmac_f32_e32 v11, v222, v222
	v_fmac_f32_e32 v11, v223, v223
	global_store_dwordx2 v2, v[24:25], s[12:13]
	global_store_dwordx2 v2, v[26:27], s[12:13] offset:512
	global_store_dwordx2 v2, v[28:29], s[12:13] offset:1024
	global_store_dwordx2 v2, v[30:31], s[12:13] offset:1536
	s_add_u32 s12, s12, 0x400000
	s_addc_u32 s13, s13, 0
	v_add_f32_dpp v12, v8, v8 row_ror:8 row_mask:0xf bank_mask:0xf
	v_add_f32_dpp v13, v9, v9 row_ror:8 row_mask:0xf bank_mask:0xf
	v_add_f32_dpp v14, v10, v10 row_ror:8 row_mask:0xf bank_mask:0xf
	v_add_f32_dpp v15, v11, v11 row_ror:8 row_mask:0xf bank_mask:0xf
	v_add_f32_dpp v8, v12, v12 row_ror:4 row_mask:0xf bank_mask:0xf
	v_add_f32_dpp v9, v13, v13 row_ror:4 row_mask:0xf bank_mask:0xf
	v_add_f32_dpp v10, v14, v14 row_ror:4 row_mask:0xf bank_mask:0xf
	v_add_f32_dpp v11, v15, v15 row_ror:4 row_mask:0xf bank_mask:0xf
	v_add_f32_dpp v12, v8, v8 row_ror:2 row_mask:0xf bank_mask:0xf
	v_add_f32_dpp v13, v9, v9 row_ror:2 row_mask:0xf bank_mask:0xf
	v_add_f32_dpp v14, v10, v10 row_ror:2 row_mask:0xf bank_mask:0xf
	v_add_f32_dpp v15, v11, v11 row_ror:2 row_mask:0xf bank_mask:0xf
	v_add_f32_dpp v8, v12, v12 row_ror:1 row_mask:0xf bank_mask:0xf
	v_add_f32_dpp v9, v13, v13 row_ror:1 row_mask:0xf bank_mask:0xf
	v_add_f32_dpp v10, v14, v14 row_ror:1 row_mask:0xf bank_mask:0xf
	v_add_f32_dpp v11, v15, v15 row_ror:1 row_mask:0xf bank_mask:0xf
	ds_bpermute_b32 v12, v4, v8
	ds_bpermute_b32 v13, v4, v9
	ds_bpermute_b32 v14, v4, v10
	ds_bpermute_b32 v15, v4, v11
	s_waitcnt lgkmcnt(0)
	v_add_f32_e32 v8, v8, v12
	v_add_f32_e32 v9, v9, v13
	v_add_f32_e32 v10, v10, v14
	v_add_f32_e32 v11, v11, v15
	ds_bpermute_b32 v12, v5, v8
	ds_bpermute_b32 v13, v5, v9
	ds_bpermute_b32 v14, v5, v10
	ds_bpermute_b32 v15, v5, v11
	s_waitcnt lgkmcnt(0)
	v_add_f32_e32 v8, v8, v12
	v_add_f32_e32 v9, v9, v13
	v_add_f32_e32 v10, v10, v14
	v_add_f32_e32 v11, v11, v15
	v_cndmask_b32_e64 v8, v6, v8, s[16:17]
	v_cndmask_b32_e64 v9, v6, v9, s[16:17]
	v_cndmask_b32_e64 v10, v6, v10, s[16:17]
	v_cndmask_b32_e64 v11, v6, v11, s[16:17]
	s_and_saveexec_b64 s[18:19], s[4:5]
	global_store_dword v3, v8, s[14:15]
	s_add_u32 s14, s14, 0x20000
	s_addc_u32 s15, s15, 0
	global_store_dword v3, v9, s[14:15]
	s_add_u32 s14, s14, 0x20000
	s_addc_u32 s15, s15, 0
	global_store_dword v3, v10, s[14:15]
	s_add_u32 s14, s14, 0x20000
	s_addc_u32 s15, s15, 0
	global_store_dword v3, v11, s[14:15]
	s_add_u32 s14, s14, 0x20000
	s_addc_u32 s15, s15, 0
	s_mov_b64 exec, s[18:19]
	global_load_dwordx4 v[160:163], v1, s[10:11] nt
	global_load_dwordx4 v[164:167], v1, s[10:11] offset:1024 nt
	global_load_dwordx4 v[168:171], v1, s[10:11] offset:2048 nt
	global_load_dwordx4 v[172:175], v1, s[10:11] offset:3072 nt
	s_add_u32 s10, s10, 0x800000
	s_addc_u32 s11, s11, 0
	global_load_dwordx4 v[176:179], v1, s[10:11] nt
	global_load_dwordx4 v[180:183], v1, s[10:11] offset:1024 nt
	global_load_dwordx4 v[184:187], v1, s[10:11] offset:2048 nt
	global_load_dwordx4 v[188:191], v1, s[10:11] offset:3072 nt
	s_add_u32 s10, s10, 0x800000
	s_addc_u32 s11, s11, 0
	global_load_dwordx4 v[192:195], v1, s[10:11] nt
	global_load_dwordx4 v[196:199], v1, s[10:11] offset:1024 nt
	global_load_dwordx4 v[200:203], v1, s[10:11] offset:2048 nt
	global_load_dwordx4 v[204:207], v1, s[10:11] offset:3072 nt
	s_add_u32 s10, s10, 0x800000
	s_addc_u32 s11, s11, 0
	global_load_dwordx4 v[208:211], v1, s[10:11] nt
	global_load_dwordx4 v[212:215], v1, s[10:11] offset:1024 nt
	global_load_dwordx4 v[216:219], v1, s[10:11] offset:2048 nt
	global_load_dwordx4 v[220:223], v1, s[10:11] offset:3072 nt
	s_add_u32 s10, s10, 0x800000
	s_addc_u32 s11, s11, 0
	s_waitcnt vmcnt(36)
; #define lane (hw_lane())
; __device__ __forceinline__ void prologue(const Args& a, LAS unsigned char* lds, int gw, int NGW, int lane, int wave) {
;     ...
;             for (int j = 0; j < 4; ++j) s += (v[j].x * v[j].x + v[j].y * v[j].y) + (v[j].z * v[j].z + v[j].w * v[j].w);
;             s = wave_sum(s);
;             float sc = 1.f;
;             if (is_mem) sc = __builtin_amdgcn_rsqf(s * (1.0f / D) + EPS);
;             else if (lane < 16) slots[(size_t)row * 16 + lane] = lane == 0 ? s : 0.f;
	v_cvt_pk_bf16_f32 v16, v40, v41
	v_cvt_pk_bf16_f32 v17, v42, v43
	v_cvt_pk_bf16_f32 v18, v44, v45
	v_cvt_pk_bf16_f32 v19, v46, v47
	v_cvt_pk_bf16_f32 v20, v48, v49
	v_cvt_pk_bf16_f32 v21, v50, v51
	v_cvt_pk_bf16_f32 v22, v52, v53
	v_cvt_pk_bf16_f32 v23, v54, v55
	v_mul_f32_e32 v8, v40, v40
	v_fmac_f32_e32 v8, v41, v41
	v_fmac_f32_e32 v8, v42, v42
	v_fmac_f32_e32 v8, v43, v43
	v_fmac_f32_e32 v8, v44, v44
	v_fmac_f32_e32 v8, v45, v45
	v_fmac_f32_e32 v8, v46, v46
	v_fmac_f32_e32 v8, v47, v47
	v_fmac_f32_e32 v8, v48, v48
	v_fmac_f32_e32 v8, v49, v49
	v_fmac_f32_e32 v8, v50, v50
	v_fmac_f32_e32 v8, v51, v51
	v_fmac_f32_e32 v8, v52, v52
	v_fmac_f32_e32 v8, v53, v53
	v_fmac_f32_e32 v8, v54, v54
	v_fmac_f32_e32 v8, v55, v55
	global_store_dwordx2 v2, v[16:17], s[12:13]
	global_store_dwordx2 v2, v[18:19], s[12:13] offset:512
	global_store_dwordx2 v2, v[20:21], s[12:13] offset:1024
	global_store_dwordx2 v2, v[22:23], s[12:13] offset:1536
	s_add_u32 s12, s12, 0x400000
	s_addc_u32 s13, s13, 0
	v_cvt_pk_bf16_f32 v24, v56, v57
	v_cvt_pk_bf16_f32 v25, v58, v59
	v_cvt_pk_bf16_f32 v26, v60, v61
	v_cvt_pk_bf16_f32 v27, v62, v63
	v_cvt_pk_bf16_f32 v28, v64, v65
	v_cvt_pk_bf16_f32 v29, v66, v67
	v_cvt_pk_bf16_f32 v30, v68, v69
	v_cvt_pk_bf16_f32 v31, v70, v71
	v_mul_f32_e32 v9, v56, v56
	v_fmac_f32_e32 v9, v57, v57
	v_fmac_f32_e32 v9, v58, v58
	v_fmac_f32_e32 v9, v59, v59
	v_fmac_f32_e32 v9, v60, v60
	v_fmac_f32_e32 v9, v61, v61
	v_fmac_f32_e32 v9, v62, v62
	v_fmac_f32_e32 v9, v63, v63
	v_fmac_f32_e32 v9, v64, v64
	v_fmac_f32_e32 v9, v65, v65
	v_fmac_f32_e32 v9, v66, v66
	v_fmac_f32_e32 v9, v67, v67
	v_fmac_f32_e32 v9, v68, v68
	v_fmac_f32_e32 v9, v69, v69
	v_fmac_f32_e32 v9, v70, v70
	v_fmac_f32_e32 v9, v71, v71
	global_store_dwordx2 v2, v[24:25], s[12:13]
	global_store_dwordx2 v2, v[26:27], s[12:13] offset:512
	global_store_dwordx2 v2, v[28:29], s[12:13] offset:1024
	global_store_dwordx2 v2, v[30:31], s[12:13] offset:1536
	s_add_u32 s12, s12, 0x400000
	s_addc_u32 s13, s13, 0
	v_cvt_pk_bf16_f32 v16, v72, v73
	v_cvt_pk_bf16_f32 v17, v74, v75
	v_cvt_pk_bf16_f32 v18, v76, v77
	v_cvt_pk_bf16_f32 v19, v78, v79
	v_cvt_pk_bf16_f32 v20, v80, v81
	v_cvt_pk_bf16_f32 v21, v82, v83
	v_cvt_pk_bf16_f32 v22, v84, v85
	v_cvt_pk_bf16_f32 v23, v86, v87
	v_mul_f32_e32 v10, v72, v72
	v_fmac_f32_e32 v10, v73, v73
	v_fmac_f32_e32 v10, v74, v74
	v_fmac_f32_e32 v10, v75, v75
	v_fmac_f32_e32 v10, v76, v76
	v_fmac_f32_e32 v10, v77, v77
	v_fmac_f32_e32 v10, v78, v78
	v_fmac_f32_e32 v10, v79, v79
	v_fmac_f32_e32 v10, v80, v80
	v_fmac_f32_e32 v10, v81, v81
	v_fmac_f32_e32 v10, v82, v82
	v_fmac_f32_e32 v10, v83, v83
	v_fmac_f32_e32 v10, v84, v84
	v_fmac_f32_e32 v10, v85, v85
	v_fmac_f32_e32 v10, v86, v86
	v_fmac_f32_e32 v10, v87, v87
	global_store_dwordx2 v2, v[16:17], s[12:13]
	global_store_dwordx2 v2, v[18:19], s[12:13] offset:512
	global_store_dwordx2 v2, v[20:21], s[12:13] offset:1024
	global_store_dwordx2 v2, v[22:23], s[12:13] offset:1536
	s_add_u32 s12, s12, 0x400000
	s_addc_u32 s13, s13, 0
	v_cvt_pk_bf16_f32 v24, v88, v89
	v_cvt_pk_bf16_f32 v25, v90, v91
	v_cvt_pk_bf16_f32 v26, v92, v93
	v_cvt_pk_bf16_f32 v27, v94, v95
	v_cvt_pk_bf16_f32 v28, v96, v97
	v_cvt_pk_bf16_f32 v29, v98, v99
	v_cvt_pk_bf16_f32 v30, v100, v101
	v_cvt_pk_bf16_f32 v31, v102, v103
	v_mul_f32_e32 v11, v88, v88
	v_fmac_f32_e32 v11, v89, v89
	v_fmac_f32_e32 v11, v90, v90
	v_fmac_f32_e32 v11, v91, v91
	v_fmac_f32_e32 v11, v92, v92
	v_fmac_f32_e32 v11, v93, v93
	v_fmac_f32_e32 v11, v94, v94
	v_fmac_f32_e32 v11, v95, v95
	v_fmac_f32_e32 v11, v96, v96
	v_fmac_f32_e32 v11, v97, v97
	v_fmac_f32_e32 v11, v98, v98
	v_fmac_f32_e32 v11, v99, v99
	v_fmac_f32_e32 v11, v100, v100
	v_fmac_f32_e32 v11, v101, v101
	v_fmac_f32_e32 v11, v102, v102
	v_fmac_f32_e32 v11, v103, v103
	global_store_dwordx2 v2, v[24:25], s[12:13]
	global_store_dwordx2 v2, v[26:27], s[12:13] offset:512
	global_store_dwordx2 v2, v[28:29], s[12:13] offset:1024
	global_store_dwordx2 v2, v[30:31], s[12:13] offset:1536
	s_add_u32 s12, s12, 0x400000
	s_addc_u32 s13, s13, 0
	v_add_f32_dpp v12, v8, v8 row_ror:8 row_mask:0xf bank_mask:0xf
	v_add_f32_dpp v13, v9, v9 row_ror:8 row_mask:0xf bank_mask:0xf
	v_add_f32_dpp v14, v10, v10 row_ror:8 row_mask:0xf bank_mask:0xf
	v_add_f32_dpp v15, v11, v11 row_ror:8 row_mask:0xf bank_mask:0xf
	v_add_f32_dpp v8, v12, v12 row_ror:4 row_mask:0xf bank_mask:0xf
	v_add_f32_dpp v9, v13, v13 row_ror:4 row_mask:0xf bank_mask:0xf
	v_add_f32_dpp v10, v14, v14 row_ror:4 row_mask:0xf bank_mask:0xf
	v_add_f32_dpp v11, v15, v15 row_ror:4 row_mask:0xf bank_mask:0xf
	v_add_f32_dpp v12, v8, v8 row_ror:2 row_mask:0xf bank_mask:0xf
	v_add_f32_dpp v13, v9, v9 row_ror:2 row_mask:0xf bank_mask:0xf
	v_add_f32_dpp v14, v10, v10 row_ror:2 row_mask:0xf bank_mask:0xf
	v_add_f32_dpp v15, v11, v11 row_ror:2 row_mask:0xf bank_mask:0xf
	v_add_f32_dpp v8, v12, v12 row_ror:1 row_mask:0xf bank_mask:0xf
	v_add_f32_dpp v9, v13, v13 row_ror:1 row_mask:0xf bank_mask:0xf
	v_add_f32_dpp v10, v14, v14 row_ror:1 row_mask:0xf bank_mask:0xf
	v_add_f32_dpp v11, v15, v15 row_ror:1 row_mask:0xf bank_mask:0xf
	ds_bpermute_b32 v12, v4, v8
	ds_bpermute_b32 v13, v4, v9
	ds_bpermute_b32 v14, v4, v10
	ds_bpermute_b32 v15, v4, v11
	s_waitcnt lgkmcnt(0)
	v_add_f32_e32 v8, v8, v12
	v_add_f32_e32 v9, v9, v13
	v_add_f32_e32 v10, v10, v14
	v_add_f32_e32 v11, v11, v15
	ds_bpermute_b32 v12, v5, v8
	ds_bpermute_b32 v13, v5, v9
	ds_bpermute_b32 v14, v5, v10
	ds_bpermute_b32 v15, v5, v11
	s_waitcnt lgkmcnt(0)
; __device__ __forceinline__ unsigned pk2(float lo, float hi) { return f2bf(lo) | (f2bf(hi) << 16); }
; #define lane (hw_lane())
; __device__ __forceinline__ void prologue(const Args& a, LAS unsigned char* lds, int gw, int NGW, int lane, int wave) {
;     ...
;                 for (int j = 0; j < 4; ++j) nv[j] = __builtin_nontemporal_load(xr + 64 * j); } }
; #pragma unroll
;             for (int j = 0; j < 4; ++j) s += (v[j].x * v[j].x + v[j].y * v[j].y) + (v[j].z * v[j].z + v[j].w * v[j].w);
;             s = wave_sum(s);
;             float sc = 1.f;
;             if (is_mem) sc = __builtin_amdgcn_rsqf(s * (1.0f / D) + EPS);
;             else if (lane < 16) slots[(size_t)row * 16 + lane] = lane == 0 ? s : 0.f;
;             v2u* o8 = (v2u*)((is_mem ? MEMN : HB) + (size_t)row * D) + lane;
; #pragma unroll
;             for (int j = 0; j < 4; ++j) { v2u o; o.x = pk2(v[j].x * sc, v[j].y * sc); o.y = pk2(v[j].z * sc, v[j].w * sc); o8[64 * j] = o; }
	v_add_f32_e32 v8, v8, v12
	v_add_f32_e32 v9, v9, v13
	v_add_f32_e32 v10, v10, v14
	v_add_f32_e32 v11, v11, v15
	v_cndmask_b32_e64 v8, v6, v8, s[16:17]
	v_cndmask_b32_e64 v9, v6, v9, s[16:17]
	v_cndmask_b32_e64 v10, v6, v10, s[16:17]
	v_cndmask_b32_e64 v11, v6, v11, s[16:17]
	s_and_saveexec_b64 s[18:19], s[4:5]
	global_store_dword v3, v8, s[14:15]
	s_add_u32 s14, s14, 0x20000
	s_addc_u32 s15, s15, 0
	global_store_dword v3, v9, s[14:15]
	s_add_u32 s14, s14, 0x20000
	s_addc_u32 s15, s15, 0
	global_store_dword v3, v10, s[14:15]
	s_add_u32 s14, s14, 0x20000
	s_addc_u32 s15, s15, 0
	global_store_dword v3, v11, s[14:15]
	s_add_u32 s14, s14, 0x20000
	s_addc_u32 s15, s15, 0
	s_mov_b64 exec, s[18:19]
	global_load_dwordx4 v[40:43], v1, s[10:11] nt
	global_load_dwordx4 v[44:47], v1, s[10:11] offset:1024 nt
	global_load_dwordx4 v[48:51], v1, s[10:11] offset:2048 nt
	global_load_dwordx4 v[52:55], v1, s[10:11] offset:3072 nt
	s_add_u32 s10, s10, 0x800000
	s_addc_u32 s11, s11, 0
	global_load_dwordx4 v[56:59], v1, s[10:11] nt
	global_load_dwordx4 v[60:63], v1, s[10:11] offset:1024 nt
	global_load_dwordx4 v[64:67], v1, s[10:11] offset:2048 nt
	global_load_dwordx4 v[68:71], v1, s[10:11] offset:3072 nt
	s_add_u32 s10, s10, 0x800000
	s_addc_u32 s11, s11, 0
	global_load_dwordx4 v[72:75], v1, s[10:11] nt
	global_load_dwordx4 v[76:79], v1, s[10:11] offset:1024 nt
	global_load_dwordx4 v[80:83], v1, s[10:11] offset:2048 nt
	global_load_dwordx4 v[84:87], v1, s[10:11] offset:3072 nt
	s_add_u32 s10, s10, 0x800000
	s_addc_u32 s11, s11, 0
	global_load_dwordx4 v[88:91], v1, s[10:11] nt
	global_load_dwordx4 v[92:95], v1, s[10:11] offset:1024 nt
	global_load_dwordx4 v[96:99], v1, s[10:11] offset:2048 nt
	global_load_dwordx4 v[100:103], v1, s[10:11] offset:3072 nt
	s_add_u32 s10, s10, 0x800000
	s_addc_u32 s11, s11, 0
	s_waitcnt vmcnt(36)
	v_cvt_pk_bf16_f32 v16, v160, v161
	v_cvt_pk_bf16_f32 v17, v162, v163
	v_cvt_pk_bf16_f32 v18, v164, v165
	v_cvt_pk_bf16_f32 v19, v166, v167
	v_cvt_pk_bf16_f32 v20, v168, v169
	v_cvt_pk_bf16_f32 v21, v170, v171
	v_cvt_pk_bf16_f32 v22, v172, v173
	v_cvt_pk_bf16_f32 v23, v174, v175
	v_mul_f32_e32 v8, v160, v160
	v_fmac_f32_e32 v8, v161, v161
	v_fmac_f32_e32 v8, v162, v162
	v_fmac_f32_e32 v8, v163, v163
	v_fmac_f32_e32 v8, v164, v164
	v_fmac_f32_e32 v8, v165, v165
	v_fmac_f32_e32 v8, v166, v166
	v_fmac_f32_e32 v8, v167, v167
	v_fmac_f32_e32 v8, v168, v168
	v_fmac_f32_e32 v8, v169, v169
	v_fmac_f32_e32 v8, v170, v170
	v_fmac_f32_e32 v8, v171, v171
	v_fmac_f32_e32 v8, v172, v172
	v_fmac_f32_e32 v8, v173, v173
	v_fmac_f32_e32 v8, v174, v174
	v_fmac_f32_e32 v8, v175, v175
	global_store_dwordx2 v2, v[16:17], s[12:13]
	global_store_dwordx2 v2, v[18:19], s[12:13] offset:512
	global_store_dwordx2 v2, v[20:21], s[12:13] offset:1024
	global_store_dwordx2 v2, v[22:23], s[12:13] offset:1536
	s_add_u32 s12, s12, 0x400000
	s_addc_u32 s13, s13, 0
	v_cvt_pk_bf16_f32 v24, v176, v177
	v_cvt_pk_bf16_f32 v25, v178, v179
	v_cvt_pk_bf16_f32 v26, v180, v181
	v_cvt_pk_bf16_f32 v27, v182, v183
	v_cvt_pk_bf16_f32 v28, v184, v185
	v_cvt_pk_bf16_f32 v29, v186, v187
	v_cvt_pk_bf16_f32 v30, v188, v189
	v_cvt_pk_bf16_f32 v31, v190, v191
	v_mul_f32_e32 v9, v176, v176
	v_fmac_f32_e32 v9, v177, v177
	v_fmac_f32_e32 v9, v178, v178
	v_fmac_f32_e32 v9, v179, v179
	v_fmac_f32_e32 v9, v180, v180
	v_fmac_f32_e32 v9, v181, v181
	v_fmac_f32_e32 v9, v182, v182
	v_fmac_f32_e32 v9, v183, v183
	v_fmac_f32_e32 v9, v184, v184
	v_fmac_f32_e32 v9, v185, v185
	v_fmac_f32_e32 v9, v186, v186
	v_fmac_f32_e32 v9, v187, v187
	v_fmac_f32_e32 v9, v188, v188
	v_fmac_f32_e32 v9, v189, v189
	v_fmac_f32_e32 v9, v190, v190
	v_fmac_f32_e32 v9, v191, v191
	global_store_dwordx2 v2, v[24:25], s[12:13]
	global_store_dwordx2 v2, v[26:27], s[12:13] offset:512
	global_store_dwordx2 v2, v[28:29], s[12:13] offset:1024
	global_store_dwordx2 v2, v[30:31], s[12:13] offset:1536
	s_add_u32 s12, s12, 0x400000
	s_addc_u32 s13, s13, 0
	v_cvt_pk_bf16_f32 v16, v192, v193
	v_cvt_pk_bf16_f32 v17, v194, v195
	v_cvt_pk_bf16_f32 v18, v196, v197
	v_cvt_pk_bf16_f32 v19, v198, v199
	v_cvt_pk_bf16_f32 v20, v200, v201
	v_cvt_pk_bf16_f32 v21, v202, v203
	v_cvt_pk_bf16_f32 v22, v204, v205
	v_cvt_pk_bf16_f32 v23, v206, v207
	v_mul_f32_e32 v10, v192, v192
	v_fmac_f32_e32 v10, v193, v193
	v_fmac_f32_e32 v10, v194, v194
	v_fmac_f32_e32 v10, v195, v195
	v_fmac_f32_e32 v10, v196, v196
	v_fmac_f32_e32 v10, v197, v197
	v_fmac_f32_e32 v10, v198, v198
	v_fmac_f32_e32 v10, v199, v199
	v_fmac_f32_e32 v10, v200, v200
	v_fmac_f32_e32 v10, v201, v201
	v_fmac_f32_e32 v10, v202, v202
	v_fmac_f32_e32 v10, v203, v203
	v_fmac_f32_e32 v10, v204, v204
	v_fmac_f32_e32 v10, v205, v205
	v_fmac_f32_e32 v10, v206, v206
	v_fmac_f32_e32 v10, v207, v207
	global_store_dwordx2 v2, v[16:17], s[12:13]
	global_store_dwordx2 v2, v[18:19], s[12:13] offset:512
	global_store_dwordx2 v2, v[20:21], s[12:13] offset:1024
	global_store_dwordx2 v2, v[22:23], s[12:13] offset:1536
	s_add_u32 s12, s12, 0x400000
	s_addc_u32 s13, s13, 0
	v_cvt_pk_bf16_f32 v24, v208, v209
	v_cvt_pk_bf16_f32 v25, v210, v211
	v_cvt_pk_bf16_f32 v26, v212, v213
	v_cvt_pk_bf16_f32 v27, v214, v215
	v_cvt_pk_bf16_f32 v28, v216, v217
	v_cvt_pk_bf16_f32 v29, v218, v219
	v_cvt_pk_bf16_f32 v30, v220, v221
	v_cvt_pk_bf16_f32 v31, v222, v223
	v_mul_f32_e32 v11, v208, v208
	v_fmac_f32_e32 v11, v209, v209
	v_fmac_f32_e32 v11, v210, v210
	v_fmac_f32_e32 v11, v211, v211
	v_fmac_f32_e32 v11, v212, v212
	v_fmac_f32_e32 v11, v213, v213
	v_fmac_f32_e32 v11, v214, v214
	v_fmac_f32_e32 v11, v215, v215
	v_fmac_f32_e32 v11, v216, v216
	v_fmac_f32_e32 v11, v217, v217
	v_fmac_f32_e32 v11, v218, v218
	v_fmac_f32_e32 v11, v219, v219
; __device__ __forceinline__ unsigned pk2(float lo, float hi) { return f2bf(lo) | (f2bf(hi) << 16); }
; #define lane (hw_lane())
; __device__ __forceinline__ void prologue(const Args& a, LAS unsigned char* lds, int gw, int NGW, int lane, int wave) {
;     ...
;                 for (int j = 0; j < 4; ++j) nv[j] = __builtin_nontemporal_load(xr + 64 * j); } }
; #pragma unroll
;             for (int j = 0; j < 4; ++j) s += (v[j].x * v[j].x + v[j].y * v[j].y) + (v[j].z * v[j].z + v[j].w * v[j].w);
;             s = wave_sum(s);
;             float sc = 1.f;
;             if (is_mem) sc = __builtin_amdgcn_rsqf(s * (1.0f / D) + EPS);
;             else if (lane < 16) slots[(size_t)row * 16 + lane] = lane == 0 ? s : 0.f;
;             v2u* o8 = (v2u*)((is_mem ? MEMN : HB) + (size_t)row * D) + lane;
; #pragma unroll
;             for (int j = 0; j < 4; ++j) { v2u o; o.x = pk2(v[j].x * sc, v[j].y * sc); o.y = pk2(v[j].z * sc, v[j].w * sc); o8[64 * j] = o; }
	v_fmac_f32_e32 v11, v220, v220
	v_fmac_f32_e32 v11, v221, v221
	v_fmac_f32_e32 v11, v222, v222
	v_fmac_f32_e32 v11, v223, v223
	global_store_dwordx2 v2, v[24:25], s[12:13]
	global_store_dwordx2 v2, v[26:27], s[12:13] offset:512
	global_store_dwordx2 v2, v[28:29], s[12:13] offset:1024
	global_store_dwordx2 v2, v[30:31], s[12:13] offset:1536
	s_add_u32 s12, s12, 0x400000
	s_addc_u32 s13, s13, 0
	v_add_f32_dpp v12, v8, v8 row_ror:8 row_mask:0xf bank_mask:0xf
	v_add_f32_dpp v13, v9, v9 row_ror:8 row_mask:0xf bank_mask:0xf
	v_add_f32_dpp v14, v10, v10 row_ror:8 row_mask:0xf bank_mask:0xf
	v_add_f32_dpp v15, v11, v11 row_ror:8 row_mask:0xf bank_mask:0xf
	v_add_f32_dpp v8, v12, v12 row_ror:4 row_mask:0xf bank_mask:0xf
	v_add_f32_dpp v9, v13, v13 row_ror:4 row_mask:0xf bank_mask:0xf
	v_add_f32_dpp v10, v14, v14 row_ror:4 row_mask:0xf bank_mask:0xf
	v_add_f32_dpp v11, v15, v15 row_ror:4 row_mask:0xf bank_mask:0xf
	v_add_f32_dpp v12, v8, v8 row_ror:2 row_mask:0xf bank_mask:0xf
	v_add_f32_dpp v13, v9, v9 row_ror:2 row_mask:0xf bank_mask:0xf
	v_add_f32_dpp v14, v10, v10 row_ror:2 row_mask:0xf bank_mask:0xf
	v_add_f32_dpp v15, v11, v11 row_ror:2 row_mask:0xf bank_mask:0xf
	v_add_f32_dpp v8, v12, v12 row_ror:1 row_mask:0xf bank_mask:0xf
	v_add_f32_dpp v9, v13, v13 row_ror:1 row_mask:0xf bank_mask:0xf
	v_add_f32_dpp v10, v14, v14 row_ror:1 row_mask:0xf bank_mask:0xf
	v_add_f32_dpp v11, v15, v15 row_ror:1 row_mask:0xf bank_mask:0xf
	ds_bpermute_b32 v12, v4, v8
	ds_bpermute_b32 v13, v4, v9
	ds_bpermute_b32 v14, v4, v10
	ds_bpermute_b32 v15, v4, v11
	s_waitcnt lgkmcnt(0)
	v_add_f32_e32 v8, v8, v12
	v_add_f32_e32 v9, v9, v13
	v_add_f32_e32 v10, v10, v14
	v_add_f32_e32 v11, v11, v15
	ds_bpermute_b32 v12, v5, v8
	ds_bpermute_b32 v13, v5, v9
	ds_bpermute_b32 v14, v5, v10
	ds_bpermute_b32 v15, v5, v11
	s_waitcnt lgkmcnt(0)
	v_add_f32_e32 v8, v8, v12
	v_add_f32_e32 v9, v9, v13
	v_add_f32_e32 v10, v10, v14
	v_add_f32_e32 v11, v11, v15
	v_cndmask_b32_e64 v8, v6, v8, s[16:17]
	v_cndmask_b32_e64 v9, v6, v9, s[16:17]
	v_cndmask_b32_e64 v10, v6, v10, s[16:17]
	v_cndmask_b32_e64 v11, v6, v11, s[16:17]
	s_and_saveexec_b64 s[18:19], s[4:5]
	global_store_dword v3, v8, s[14:15]
	s_add_u32 s14, s14, 0x20000
	s_addc_u32 s15, s15, 0
	global_store_dword v3, v9, s[14:15]
	s_add_u32 s14, s14, 0x20000
	s_addc_u32 s15, s15, 0
	global_store_dword v3, v10, s[14:15]
	s_add_u32 s14, s14, 0x20000
	s_addc_u32 s15, s15, 0
	global_store_dword v3, v11, s[14:15]
	s_add_u32 s14, s14, 0x20000
	s_addc_u32 s15, s15, 0
	s_mov_b64 exec, s[18:19]
	global_load_dwordx4 v[160:163], v1, s[10:11] nt
	global_load_dwordx4 v[164:167], v1, s[10:11] offset:1024 nt
	global_load_dwordx4 v[168:171], v1, s[10:11] offset:2048 nt
	global_load_dwordx4 v[172:175], v1, s[10:11] offset:3072 nt
	s_add_u32 s10, s10, 0x800000
	s_addc_u32 s11, s11, 0
	global_load_dwordx4 v[176:179], v1, s[10:11] nt
	global_load_dwordx4 v[180:183], v1, s[10:11] offset:1024 nt
	global_load_dwordx4 v[184:187], v1, s[10:11] offset:2048 nt
	global_load_dwordx4 v[188:191], v1, s[10:11] offset:3072 nt
	s_add_u32 s10, s10, 0x800000
	s_addc_u32 s11, s11, 0
	global_load_dwordx4 v[192:195], v1, s[10:11] nt
	global_load_dwordx4 v[196:199], v1, s[10:11] offset:1024 nt
	global_load_dwordx4 v[200:203], v1, s[10:11] offset:2048 nt
	global_load_dwordx4 v[204:207], v1, s[10:11] offset:3072 nt
	s_add_u32 s10, s10, 0x800000
	s_addc_u32 s11, s11, 0
	global_load_dwordx4 v[208:211], v1, s[10:11] nt
	global_load_dwordx4 v[212:215], v1, s[10:11] offset:1024 nt
	global_load_dwordx4 v[216:219], v1, s[10:11] offset:2048 nt
	global_load_dwordx4 v[220:223], v1, s[10:11] offset:3072 nt
	s_add_u32 s10, s10, 0x800000
	s_addc_u32 s11, s11, 0
	s_waitcnt vmcnt(36)
	v_cvt_pk_bf16_f32 v16, v40, v41
	v_cvt_pk_bf16_f32 v17, v42, v43
	v_cvt_pk_bf16_f32 v18, v44, v45
	v_cvt_pk_bf16_f32 v19, v46, v47
	v_cvt_pk_bf16_f32 v20, v48, v49
	v_cvt_pk_bf16_f32 v21, v50, v51
	v_cvt_pk_bf16_f32 v22, v52, v53
	v_cvt_pk_bf16_f32 v23, v54, v55
	v_mul_f32_e32 v8, v40, v40
	v_fmac_f32_e32 v8, v41, v41
	v_fmac_f32_e32 v8, v42, v42
	v_fmac_f32_e32 v8, v43, v43
	v_fmac_f32_e32 v8, v44, v44
	v_fmac_f32_e32 v8, v45, v45
	v_fmac_f32_e32 v8, v46, v46
	v_fmac_f32_e32 v8, v47, v47
	v_fmac_f32_e32 v8, v48, v48
	v_fmac_f32_e32 v8, v49, v49
	v_fmac_f32_e32 v8, v50, v50
	v_fmac_f32_e32 v8, v51, v51
	v_fmac_f32_e32 v8, v52, v52
	v_fmac_f32_e32 v8, v53, v53
	v_fmac_f32_e32 v8, v54, v54
	v_fmac_f32_e32 v8, v55, v55
	global_store_dwordx2 v2, v[16:17], s[12:13]
	global_store_dwordx2 v2, v[18:19], s[12:13] offset:512
	global_store_dwordx2 v2, v[20:21], s[12:13] offset:1024
	global_store_dwordx2 v2, v[22:23], s[12:13] offset:1536
	s_add_u32 s12, s12, 0x400000
	s_addc_u32 s13, s13, 0
	v_cvt_pk_bf16_f32 v24, v56, v57
	v_cvt_pk_bf16_f32 v25, v58, v59
	v_cvt_pk_bf16_f32 v26, v60, v61
	v_cvt_pk_bf16_f32 v27, v62, v63
	v_cvt_pk_bf16_f32 v28, v64, v65
	v_cvt_pk_bf16_f32 v29, v66, v67
	v_cvt_pk_bf16_f32 v30, v68, v69
	v_cvt_pk_bf16_f32 v31, v70, v71
	v_mul_f32_e32 v9, v56, v56
	v_fmac_f32_e32 v9, v57, v57
	v_fmac_f32_e32 v9, v58, v58
	v_fmac_f32_e32 v9, v59, v59
	v_fmac_f32_e32 v9, v60, v60
	v_fmac_f32_e32 v9, v61, v61
	v_fmac_f32_e32 v9, v62, v62
	v_fmac_f32_e32 v9, v63, v63
	v_fmac_f32_e32 v9, v64, v64
	v_fmac_f32_e32 v9, v65, v65
	v_fmac_f32_e32 v9, v66, v66
	v_fmac_f32_e32 v9, v67, v67
	v_fmac_f32_e32 v9, v68, v68
	v_fmac_f32_e32 v9, v69, v69
	v_fmac_f32_e32 v9, v70, v70
	v_fmac_f32_e32 v9, v71, v71
	global_store_dwordx2 v2, v[24:25], s[12:13]
	global_store_dwordx2 v2, v[26:27], s[12:13] offset:512
	global_store_dwordx2 v2, v[28:29], s[12:13] offset:1024
	global_store_dwordx2 v2, v[30:31], s[12:13] offset:1536
; #define lane (hw_lane())
; __device__ __forceinline__ void prologue(const Args& a, LAS unsigned char* lds, int gw, int NGW, int lane, int wave) {
;     ...
;                 for (int j = 0; j < 4; ++j) nv[j] = __builtin_nontemporal_load(xr + 64 * j); } }
; #pragma unroll
;             for (int j = 0; j < 4; ++j) s += (v[j].x * v[j].x + v[j].y * v[j].y) + (v[j].z * v[j].z + v[j].w * v[j].w);
;             s = wave_sum(s);
;             float sc = 1.f;
;             if (is_mem) sc = __builtin_amdgcn_rsqf(s * (1.0f / D) + EPS);
;             else if (lane < 16) slots[(size_t)row * 16 + lane] = lane == 0 ? s : 0.f;
	s_add_u32 s12, s12, 0x400000
	s_addc_u32 s13, s13, 0
	v_cvt_pk_bf16_f32 v16, v72, v73
	v_cvt_pk_bf16_f32 v17, v74, v75
	v_cvt_pk_bf16_f32 v18, v76, v77
	v_cvt_pk_bf16_f32 v19, v78, v79
	v_cvt_pk_bf16_f32 v20, v80, v81
	v_cvt_pk_bf16_f32 v21, v82, v83
	v_cvt_pk_bf16_f32 v22, v84, v85
	v_cvt_pk_bf16_f32 v23, v86, v87
	v_mul_f32_e32 v10, v72, v72
	v_fmac_f32_e32 v10, v73, v73
	v_fmac_f32_e32 v10, v74, v74
	v_fmac_f32_e32 v10, v75, v75
	v_fmac_f32_e32 v10, v76, v76
	v_fmac_f32_e32 v10, v77, v77
	v_fmac_f32_e32 v10, v78, v78
	v_fmac_f32_e32 v10, v79, v79
	v_fmac_f32_e32 v10, v80, v80
	v_fmac_f32_e32 v10, v81, v81
	v_fmac_f32_e32 v10, v82, v82
	v_fmac_f32_e32 v10, v83, v83
	v_fmac_f32_e32 v10, v84, v84
	v_fmac_f32_e32 v10, v85, v85
	v_fmac_f32_e32 v10, v86, v86
	v_fmac_f32_e32 v10, v87, v87
	global_store_dwordx2 v2, v[16:17], s[12:13]
	global_store_dwordx2 v2, v[18:19], s[12:13] offset:512
	global_store_dwordx2 v2, v[20:21], s[12:13] offset:1024
	global_store_dwordx2 v2, v[22:23], s[12:13] offset:1536
	s_add_u32 s12, s12, 0x400000
	s_addc_u32 s13, s13, 0
	v_cvt_pk_bf16_f32 v24, v88, v89
	v_cvt_pk_bf16_f32 v25, v90, v91
	v_cvt_pk_bf16_f32 v26, v92, v93
	v_cvt_pk_bf16_f32 v27, v94, v95
	v_cvt_pk_bf16_f32 v28, v96, v97
	v_cvt_pk_bf16_f32 v29, v98, v99
	v_cvt_pk_bf16_f32 v30, v100, v101
	v_cvt_pk_bf16_f32 v31, v102, v103
	v_mul_f32_e32 v11, v88, v88
	v_fmac_f32_e32 v11, v89, v89
	v_fmac_f32_e32 v11, v90, v90
	v_fmac_f32_e32 v11, v91, v91
	v_fmac_f32_e32 v11, v92, v92
	v_fmac_f32_e32 v11, v93, v93
	v_fmac_f32_e32 v11, v94, v94
	v_fmac_f32_e32 v11, v95, v95
	v_fmac_f32_e32 v11, v96, v96
	v_fmac_f32_e32 v11, v97, v97
	v_fmac_f32_e32 v11, v98, v98
	v_fmac_f32_e32 v11, v99, v99
	v_fmac_f32_e32 v11, v100, v100
	v_fmac_f32_e32 v11, v101, v101
	v_fmac_f32_e32 v11, v102, v102
	v_fmac_f32_e32 v11, v103, v103
	global_store_dwordx2 v2, v[24:25], s[12:13]
	global_store_dwordx2 v2, v[26:27], s[12:13] offset:512
	global_store_dwordx2 v2, v[28:29], s[12:13] offset:1024
	global_store_dwordx2 v2, v[30:31], s[12:13] offset:1536
	s_add_u32 s12, s12, 0x400000
	s_addc_u32 s13, s13, 0
	v_add_f32_dpp v12, v8, v8 row_ror:8 row_mask:0xf bank_mask:0xf
	v_add_f32_dpp v13, v9, v9 row_ror:8 row_mask:0xf bank_mask:0xf
	v_add_f32_dpp v14, v10, v10 row_ror:8 row_mask:0xf bank_mask:0xf
	v_add_f32_dpp v15, v11, v11 row_ror:8 row_mask:0xf bank_mask:0xf
	v_add_f32_dpp v8, v12, v12 row_ror:4 row_mask:0xf bank_mask:0xf
	v_add_f32_dpp v9, v13, v13 row_ror:4 row_mask:0xf bank_mask:0xf
	v_add_f32_dpp v10, v14, v14 row_ror:4 row_mask:0xf bank_mask:0xf
	v_add_f32_dpp v11, v15, v15 row_ror:4 row_mask:0xf bank_mask:0xf
	v_add_f32_dpp v12, v8, v8 row_ror:2 row_mask:0xf bank_mask:0xf
	v_add_f32_dpp v13, v9, v9 row_ror:2 row_mask:0xf bank_mask:0xf
	v_add_f32_dpp v14, v10, v10 row_ror:2 row_mask:0xf bank_mask:0xf
	v_add_f32_dpp v15, v11, v11 row_ror:2 row_mask:0xf bank_mask:0xf
	v_add_f32_dpp v8, v12, v12 row_ror:1 row_mask:0xf bank_mask:0xf
	v_add_f32_dpp v9, v13, v13 row_ror:1 row_mask:0xf bank_mask:0xf
	v_add_f32_dpp v10, v14, v14 row_ror:1 row_mask:0xf bank_mask:0xf
	v_add_f32_dpp v11, v15, v15 row_ror:1 row_mask:0xf bank_mask:0xf
	ds_bpermute_b32 v12, v4, v8
	ds_bpermute_b32 v13, v4, v9
	ds_bpermute_b32 v14, v4, v10
	ds_bpermute_b32 v15, v4, v11
	s_waitcnt lgkmcnt(0)
	v_add_f32_e32 v8, v8, v12
	v_add_f32_e32 v9, v9, v13
	v_add_f32_e32 v10, v10, v14
	v_add_f32_e32 v11, v11, v15
	ds_bpermute_b32 v12, v5, v8
	ds_bpermute_b32 v13, v5, v9
	ds_bpermute_b32 v14, v5, v10
	ds_bpermute_b32 v15, v5, v11
	s_waitcnt lgkmcnt(0)
	v_add_f32_e32 v8, v8, v12
	v_add_f32_e32 v9, v9, v13
	v_add_f32_e32 v10, v10, v14
	v_add_f32_e32 v11, v11, v15
	v_cndmask_b32_e64 v8, v6, v8, s[16:17]
	v_cndmask_b32_e64 v9, v6, v9, s[16:17]
	v_cndmask_b32_e64 v10, v6, v10, s[16:17]
	v_cndmask_b32_e64 v11, v6, v11, s[16:17]
	s_and_saveexec_b64 s[18:19], s[4:5]
	global_store_dword v3, v8, s[14:15]
	s_add_u32 s14, s14, 0x20000
	s_addc_u32 s15, s15, 0
	global_store_dword v3, v9, s[14:15]
	s_add_u32 s14, s14, 0x20000
	s_addc_u32 s15, s15, 0
	global_store_dword v3, v10, s[14:15]
	s_add_u32 s14, s14, 0x20000
	s_addc_u32 s15, s15, 0
	global_store_dword v3, v11, s[14:15]
	s_add_u32 s14, s14, 0x20000
	s_addc_u32 s15, s15, 0
	s_mov_b64 exec, s[18:19]
	s_waitcnt vmcnt(20)
; #define lane (hw_lane())
; __device__ __forceinline__ void prologue(const Args& a, LAS unsigned char* lds, int gw, int NGW, int lane, int wave) {
;     ...
;         for (int m = gw; m < M + MMEM; m += NGW) {
;     ...
;             for (int j = 0; j < 4; ++j) s += (v[j].x * v[j].x + v[j].y * v[j].y) + (v[j].z * v[j].z + v[j].w * v[j].w);
;             s = wave_sum(s);
;             float sc = 1.f;
;             if (is_mem) sc = __builtin_amdgcn_rsqf(s * (1.0f / D) + EPS);
;             else if (lane < 16) slots[(size_t)row * 16 + lane] = lane == 0 ? s : 0.f;
	v_cvt_pk_bf16_f32 v16, v160, v161
	v_cvt_pk_bf16_f32 v17, v162, v163
	v_cvt_pk_bf16_f32 v18, v164, v165
	v_cvt_pk_bf16_f32 v19, v166, v167
	v_cvt_pk_bf16_f32 v20, v168, v169
	v_cvt_pk_bf16_f32 v21, v170, v171
	v_cvt_pk_bf16_f32 v22, v172, v173
	v_cvt_pk_bf16_f32 v23, v174, v175
	v_mul_f32_e32 v8, v160, v160
	v_fmac_f32_e32 v8, v161, v161
	v_fmac_f32_e32 v8, v162, v162
	v_fmac_f32_e32 v8, v163, v163
	v_fmac_f32_e32 v8, v164, v164
	v_fmac_f32_e32 v8, v165, v165
	v_fmac_f32_e32 v8, v166, v166
	v_fmac_f32_e32 v8, v167, v167
	v_fmac_f32_e32 v8, v168, v168
	v_fmac_f32_e32 v8, v169, v169
	v_fmac_f32_e32 v8, v170, v170
	v_fmac_f32_e32 v8, v171, v171
	v_fmac_f32_e32 v8, v172, v172
	v_fmac_f32_e32 v8, v173, v173
	v_fmac_f32_e32 v8, v174, v174
	v_fmac_f32_e32 v8, v175, v175
	global_store_dwordx2 v2, v[16:17], s[12:13]
	global_store_dwordx2 v2, v[18:19], s[12:13] offset:512
	global_store_dwordx2 v2, v[20:21], s[12:13] offset:1024
	global_store_dwordx2 v2, v[22:23], s[12:13] offset:1536
	s_add_u32 s12, s12, 0x400000
	s_addc_u32 s13, s13, 0
	v_cvt_pk_bf16_f32 v24, v176, v177
	v_cvt_pk_bf16_f32 v25, v178, v179
	v_cvt_pk_bf16_f32 v26, v180, v181
	v_cvt_pk_bf16_f32 v27, v182, v183
	v_cvt_pk_bf16_f32 v28, v184, v185
	v_cvt_pk_bf16_f32 v29, v186, v187
	v_cvt_pk_bf16_f32 v30, v188, v189
	v_cvt_pk_bf16_f32 v31, v190, v191
	v_mul_f32_e32 v9, v176, v176
	v_fmac_f32_e32 v9, v177, v177
	v_fmac_f32_e32 v9, v178, v178
	v_fmac_f32_e32 v9, v179, v179
	v_fmac_f32_e32 v9, v180, v180
	v_fmac_f32_e32 v9, v181, v181
	v_fmac_f32_e32 v9, v182, v182
	v_fmac_f32_e32 v9, v183, v183
	v_fmac_f32_e32 v9, v184, v184
	v_fmac_f32_e32 v9, v185, v185
	v_fmac_f32_e32 v9, v186, v186
	v_fmac_f32_e32 v9, v187, v187
	v_fmac_f32_e32 v9, v188, v188
	v_fmac_f32_e32 v9, v189, v189
	v_fmac_f32_e32 v9, v190, v190
	v_fmac_f32_e32 v9, v191, v191
	global_store_dwordx2 v2, v[24:25], s[12:13]
	global_store_dwordx2 v2, v[26:27], s[12:13] offset:512
	global_store_dwordx2 v2, v[28:29], s[12:13] offset:1024
	global_store_dwordx2 v2, v[30:31], s[12:13] offset:1536
	s_add_u32 s12, s12, 0x400000
	s_addc_u32 s13, s13, 0
	v_cvt_pk_bf16_f32 v16, v192, v193
	v_cvt_pk_bf16_f32 v17, v194, v195
	v_cvt_pk_bf16_f32 v18, v196, v197
	v_cvt_pk_bf16_f32 v19, v198, v199
	v_cvt_pk_bf16_f32 v20, v200, v201
	v_cvt_pk_bf16_f32 v21, v202, v203
	v_cvt_pk_bf16_f32 v22, v204, v205
	v_cvt_pk_bf16_f32 v23, v206, v207
	v_mul_f32_e32 v10, v192, v192
	v_fmac_f32_e32 v10, v193, v193
	v_fmac_f32_e32 v10, v194, v194
	v_fmac_f32_e32 v10, v195, v195
	v_fmac_f32_e32 v10, v196, v196
	v_fmac_f32_e32 v10, v197, v197
	v_fmac_f32_e32 v10, v198, v198
	v_fmac_f32_e32 v10, v199, v199
	v_fmac_f32_e32 v10, v200, v200
	v_fmac_f32_e32 v10, v201, v201
	v_fmac_f32_e32 v10, v202, v202
	v_fmac_f32_e32 v10, v203, v203
	v_fmac_f32_e32 v10, v204, v204
	v_fmac_f32_e32 v10, v205, v205
	v_fmac_f32_e32 v10, v206, v206
	v_fmac_f32_e32 v10, v207, v207
	global_store_dwordx2 v2, v[16:17], s[12:13]
	global_store_dwordx2 v2, v[18:19], s[12:13] offset:512
	global_store_dwordx2 v2, v[20:21], s[12:13] offset:1024
	global_store_dwordx2 v2, v[22:23], s[12:13] offset:1536
	s_add_u32 s12, s12, 0x400000
	s_addc_u32 s13, s13, 0
	v_cvt_pk_bf16_f32 v24, v208, v209
	v_cvt_pk_bf16_f32 v25, v210, v211
	v_cvt_pk_bf16_f32 v26, v212, v213
	v_cvt_pk_bf16_f32 v27, v214, v215
	v_cvt_pk_bf16_f32 v28, v216, v217
	v_cvt_pk_bf16_f32 v29, v218, v219
	v_cvt_pk_bf16_f32 v30, v220, v221
	v_cvt_pk_bf16_f32 v31, v222, v223
	v_mul_f32_e32 v11, v208, v208
	v_fmac_f32_e32 v11, v209, v209
	v_fmac_f32_e32 v11, v210, v210
	v_fmac_f32_e32 v11, v211, v211
	v_fmac_f32_e32 v11, v212, v212
	v_fmac_f32_e32 v11, v213, v213
	v_fmac_f32_e32 v11, v214, v214
	v_fmac_f32_e32 v11, v215, v215
	v_fmac_f32_e32 v11, v216, v216
	v_fmac_f32_e32 v11, v217, v217
	v_fmac_f32_e32 v11, v218, v218
	v_fmac_f32_e32 v11, v219, v219
	v_fmac_f32_e32 v11, v220, v220
	v_fmac_f32_e32 v11, v221, v221
	v_fmac_f32_e32 v11, v222, v222
	v_fmac_f32_e32 v11, v223, v223
	global_store_dwordx2 v2, v[24:25], s[12:13]
	global_store_dwordx2 v2, v[26:27], s[12:13] offset:512
	global_store_dwordx2 v2, v[28:29], s[12:13] offset:1024
	global_store_dwordx2 v2, v[30:31], s[12:13] offset:1536
	s_add_u32 s12, s12, 0x400000
	s_addc_u32 s13, s13, 0
	v_add_f32_dpp v12, v8, v8 row_ror:8 row_mask:0xf bank_mask:0xf
	v_add_f32_dpp v13, v9, v9 row_ror:8 row_mask:0xf bank_mask:0xf
	v_add_f32_dpp v14, v10, v10 row_ror:8 row_mask:0xf bank_mask:0xf
	v_add_f32_dpp v15, v11, v11 row_ror:8 row_mask:0xf bank_mask:0xf
	v_add_f32_dpp v8, v12, v12 row_ror:4 row_mask:0xf bank_mask:0xf
	v_add_f32_dpp v9, v13, v13 row_ror:4 row_mask:0xf bank_mask:0xf
	v_add_f32_dpp v10, v14, v14 row_ror:4 row_mask:0xf bank_mask:0xf
	v_add_f32_dpp v11, v15, v15 row_ror:4 row_mask:0xf bank_mask:0xf
	v_add_f32_dpp v12, v8, v8 row_ror:2 row_mask:0xf bank_mask:0xf
	v_add_f32_dpp v13, v9, v9 row_ror:2 row_mask:0xf bank_mask:0xf
	v_add_f32_dpp v14, v10, v10 row_ror:2 row_mask:0xf bank_mask:0xf
	v_add_f32_dpp v15, v11, v11 row_ror:2 row_mask:0xf bank_mask:0xf
	v_add_f32_dpp v8, v12, v12 row_ror:1 row_mask:0xf bank_mask:0xf
	v_add_f32_dpp v9, v13, v13 row_ror:1 row_mask:0xf bank_mask:0xf
	v_add_f32_dpp v10, v14, v14 row_ror:1 row_mask:0xf bank_mask:0xf
	v_add_f32_dpp v11, v15, v15 row_ror:1 row_mask:0xf bank_mask:0xf
	ds_bpermute_b32 v12, v4, v8
	ds_bpermute_b32 v13, v4, v9
	ds_bpermute_b32 v14, v4, v10
	ds_bpermute_b32 v15, v4, v11
	s_waitcnt lgkmcnt(0)
	v_add_f32_e32 v8, v8, v12
	v_add_f32_e32 v9, v9, v13
	v_add_f32_e32 v10, v10, v14
	v_add_f32_e32 v11, v11, v15
	ds_bpermute_b32 v12, v5, v8
	ds_bpermute_b32 v13, v5, v9
	ds_bpermute_b32 v14, v5, v10
	ds_bpermute_b32 v15, v5, v11
	s_waitcnt lgkmcnt(0)
	v_add_f32_e32 v8, v8, v12
	v_add_f32_e32 v9, v9, v13
	v_add_f32_e32 v10, v10, v14
	v_add_f32_e32 v11, v11, v15
	v_cndmask_b32_e64 v8, v6, v8, s[16:17]
	v_cndmask_b32_e64 v9, v6, v9, s[16:17]
	v_cndmask_b32_e64 v10, v6, v10, s[16:17]
	v_cndmask_b32_e64 v11, v6, v11, s[16:17]
	s_and_saveexec_b64 s[18:19], s[4:5]
	global_store_dword v3, v8, s[14:15]
	s_add_u32 s14, s14, 0x20000
	s_addc_u32 s15, s15, 0
	global_store_dword v3, v9, s[14:15]
	s_add_u32 s14, s14, 0x20000
	s_addc_u32 s15, s15, 0
	global_store_dword v3, v10, s[14:15]
	s_add_u32 s14, s14, 0x20000
	s_addc_u32 s15, s15, 0
	global_store_dword v3, v11, s[14:15]
	s_add_u32 s14, s14, 0x20000
	s_addc_u32 s15, s15, 0
	s_mov_b64 exec, s[18:19]
	s_lshl_b32 s98, s38, 5
	s_add_i32 s72, s72, s98
; #define lane (hw_lane())
; __device__ __forceinline__ void prologue(const Args& a, LAS unsigned char* lds, int gw, int NGW, int lane, int wave) {
;     ...
;         { const int m = gw; if (m < M + MMEM) { const f32x4* xr = (const f32x4*)((m >= M ? a.in[I_MEM] + (size_t)(m - M) * D : a.in[I_X] + (size_t)m * D)) + lane;
; #pragma unroll
;             for (int j = 0; j < 4; ++j) nv[j] = __builtin_nontemporal_load(xr + 64 * j); } }
;         for (int m = gw; m < M + MMEM; m += NGW) {
;             const bool is_mem = m >= M; const int row = is_mem ? m - M : m;
;             f32x4 v[4]; float s = 0.f;
; #pragma unroll
;             for (int j = 0; j < 4; ++j) v[j] = nv[j];
;             { const int mn = m + NGW; if (mn < M + MMEM) { const f32x4* xr = (const f32x4*)((mn >= M ? a.in[I_MEM] + (size_t)(mn - M) * D : a.in[I_X] + (size_t)mn * D)) + lane;
; #pragma unroll
;                 for (int j = 0; j < 4; ++j) nv[j] = __builtin_nontemporal_load(xr + 64 * j); } }
; #pragma unroll
;             for (int j = 0; j < 4; ++j) s += (v[j].x * v[j].x + v[j].y * v[j].y) + (v[j].z * v[j].z + v[j].w * v[j].w);
;             s = wave_sum(s);
.Lxh_skip:
	s_cmp_lt_i32 s72, 0x10800
	v_mbcnt_lo_u32_b32 v158, -1, 0
	s_cbranch_scc0 .LBB0_211
	s_ashr_i32 s73, s72, 31
	s_add_i32 s0, s72, 0xffff0000
	s_cmp_gt_i32 s72, 0xffff
	v_readlane_b32 s12, v253, 20
	s_cselect_b32 s1, 0, s73
	s_cselect_b32 s0, s0, s72
	v_readlane_b32 s13, v253, 21
	v_readlane_b32 s14, v253, 22
	v_readlane_b32 s15, v253, 23
	s_cselect_b32 s3, s15, s13
	s_cselect_b32 s4, s14, s12
	s_lshl_b64 s[0:1], s[0:1], 12
	s_add_u32 s0, s4, s0
	s_addc_u32 s1, s3, s1
	v_ashrrev_i32_e32 v37, 31, v36
	v_lshl_add_u64 v[18:19], v[36:37], 4, s[0:1]
	global_load_dwordx4 v[2:5], v[18:19], off offset:3072 nt
	global_load_dwordx4 v[6:9], v[18:19], off offset:2048 nt
	global_load_dwordx4 v[10:13], v[18:19], off offset:1024 nt
	global_load_dwordx4 v[14:17], v[18:19], off nt
	v_mbcnt_hi_u32_b32 v18, -1, v158
	v_and_b32_e32 v19, 64, v18
	v_xor_b32_e32 v20, 1, v18
	v_add_u32_e32 v19, 64, v19
	v_xor_b32_e32 v21, 2, v18
	v_cmp_lt_i32_e32 vcc, v20, v19
	v_xor_b32_e32 v22, 4, v18
	v_xor_b32_e32 v23, 8, v18
	v_cndmask_b32_e32 v20, v18, v20, vcc
	v_cmp_lt_i32_e32 vcc, v21, v19
	v_xor_b32_e32 v24, 16, v18
	v_xor_b32_e32 v25, 32, v18
	v_cndmask_b32_e32 v21, v18, v21, vcc
	v_cmp_lt_i32_e32 vcc, v22, v19
	s_lshl_b64 s[10:11], s[72:73], 6
	s_add_u32 s10, s58, s10
	v_cndmask_b32_e32 v22, v18, v22, vcc
	v_cmp_lt_i32_e32 vcc, v23, v19
	s_addc_u32 s11, s59, s11
	v_readlane_b32 s17, v253, 25
	v_cndmask_b32_e32 v23, v18, v23, vcc
	v_cmp_lt_i32_e32 vcc, v24, v19
	s_mov_b64 s[12:13], 0x5500000
	v_readlane_b32 s16, v253, 24
	v_cndmask_b32_e32 v24, v18, v24, vcc
	v_cmp_lt_i32_e32 vcc, v25, v19
	v_readlane_b32 s18, v253, 26
	v_lshlrev_b32_e32 v41, 2, v20
	v_cndmask_b32_e32 v18, v18, v25, vcc
	v_lshlrev_b32_e32 v46, 2, v18
	v_lshl_add_u64 v[18:19], v[36:37], 2, s[10:11]
	v_lshlrev_b32_e32 v42, 2, v21
	v_lshlrev_b32_e32 v43, 2, v22
	v_lshlrev_b32_e32 v44, 2, v23
	v_lshlrev_b32_e32 v45, 2, v24
	s_ashr_i32 s39, s38, 31
	s_add_i32 s17, s72, s38
	v_lshl_add_u64 v[38:39], v[18:19], 0, s[12:13]
	v_cmp_gt_i32_e64 s[0:1], 16, v36
	v_cmp_eq_u32_e64 s[4:5], 0, v36
	v_mov_b32_e32 v1, 0x358637bd
	s_movk_i32 s3, 0x7fff
	v_mov_b32_e32 v35, 1
	s_mov_b32 s16, s72
	s_lshl_b64 s[10:11], s[38:39], 6
	s_ashr_i32 s18, s17, 31
	v_readlane_b32 s19, v253, 27
	v_readlane_b32 s20, v253, 28
	v_readlane_b32 s21, v253, 29
	v_readlane_b32 s22, v253, 30
	v_readlane_b32 s23, v253, 31
	v_readlane_b32 s24, v253, 32
	v_readlane_b32 s25, v253, 33
	v_readlane_b32 s26, v253, 34
	v_readlane_b32 s27, v253, 35
	s_waitcnt vmcnt(0)
	v_mov_b64_e32 v[20:21], v[4:5]
	v_mov_b64_e32 v[24:25], v[8:9]
	v_mov_b64_e32 v[28:29], v[12:13]
	v_mov_b64_e32 v[32:33], v[16:17]
	v_mov_b64_e32 v[18:19], v[2:3]
	v_mov_b64_e32 v[22:23], v[6:7]
	v_mov_b64_e32 v[26:27], v[10:11]
	v_mov_b64_e32 v[30:31], v[14:15]
	s_branch .LBB0_203

; __device__ __forceinline__ void prologue(const Args& a, LAS unsigned char* lds, int gw, int NGW, int lane, int wave) {
;     ...
;         }
;     }
; __global__ void __launch_bounds__(512, 2) fwd_megakernel(Args a) {
;     ...
;     grid.sync();
.LBB0_211:
	s_sub_i32 s72, s72, s98
	v_bfe_u32 v2, v0, 10, 10
	v_bfe_u32 v3, v0, 20, 10
	v_or3_b32 v0, v34, v2, v3
	v_cmp_eq_u32_e32 vcc, 0, v0
	s_waitcnt lgkmcnt(0)
	s_barrier
	s_and_saveexec_b64 s[0:1], vcc
	s_xor_b64 s[0:1], exec, s[0:1]
	s_cbranch_execz .LBB0_221
	buffer_wbl2 sc1
	s_waitcnt vmcnt(0)
	s_load_dwordx2 s[4:5], s[6:7], 0x58
	v_mov_b32_e32 v4, 0
	s_mov_b64 s[10:11], exec
	v_mbcnt_lo_u32_b32 v1, s10, 0
	v_mbcnt_hi_u32_b32 v1, s11, v1
	s_waitcnt lgkmcnt(0)
	global_load_dword v0, v4, s[4:5] offset:40
	v_cmp_eq_u32_e32 vcc, 0, v1
	s_and_saveexec_b64 s[12:13], vcc
	s_cbranch_execz .LBB0_214
	s_bcnt1_i32_b64 s3, s[10:11]
	v_mov_b32_e32 v5, s3
	global_atomic_add v5, v4, v5, s[4:5] offset:32 sc0
